# removed 124 dead pointer SALU instructions in sg part 3 (their loads were already hoisted), on the non-GEMM latency stack
# speedup vs baseline: 1.0008x; 1.0008x over previous
; __device__ __forceinline__ void sg_item(int l, int chunk, LAS unsigned char* lds, const bf16_t* UB, const bf16_t* V2T, bf16_t* YC1, const bf16_t* Wb,
;                                         const float* sg_ln_g, const float* sg_ln_b, const float* sg_b, int lane, int wave) {
;     ...
;         const int th = wave & 1, cq = wave >> 1, s = 64 * th + lane;
;         const bf16_t* src = V2T + ((size_t)b * BW + 64 * cq) * SEQ + pos0;
;         float v[64]; float sum = 0.f, sq = 0.f;
; #pragma unroll
;         for (int cb = 0; cb < 64; cb += 8) {
;             unsigned raw[8]; const void* pp[8];
; #pragma unroll
;             for (int j = 0; j < 8; ++j) pp[j] = src + (size_t)(cb + j) * SEQ;
;             ld_u16_s8(raw, (unsigned)s * 2u, pp);
; #pragma unroll
;             for (int j = 0; j < 8; ++j) v[cb + j] = __uint_as_float(raw[j] << 16);
;         }
.LBB0_79:
	s_and_b32 s12, s88, 0xf80
	s_and_b32 s1, s85, 0x7ffff
	s_and_b32 s0, s84, 0xffffff00
	s_add_u32 s0, s0, s15
	s_addc_u32 s1, s1, s46
	s_lshl_b64 s[0:1], s[0:1], 13
	s_add_u32 s0, s2, s0
	s_addc_u32 s1, s3, s1
	s_lshl_b32 s12, s12, 1
	s_add_u32 s0, s0, s12
	s_addc_u32 s1, s1, 0
	s_mov_b64 s[48:49], s[0:1]
	s_nop 4
	global_load_ushort v132, v149, s[48:49]
	s_add_u32 s48, s48, 0x2000
	s_addc_u32 s49, s49, 0
	global_load_ushort v133, v149, s[48:49]
	s_add_u32 s48, s48, 0x2000
	s_addc_u32 s49, s49, 0
	global_load_ushort v130, v149, s[48:49]
	s_add_u32 s48, s48, 0x2000
	s_addc_u32 s49, s49, 0
	global_load_ushort v128, v149, s[48:49]
	s_add_u32 s48, s48, 0x2000
	s_addc_u32 s49, s49, 0
	global_load_ushort v126, v149, s[48:49]
	s_add_u32 s48, s48, 0x2000
	s_addc_u32 s49, s49, 0
	global_load_ushort v124, v149, s[48:49]
	s_add_u32 s48, s48, 0x2000
	s_addc_u32 s49, s49, 0
	global_load_ushort v120, v149, s[48:49]
	s_add_u32 s48, s48, 0x2000
	s_addc_u32 s49, s49, 0
	global_load_ushort v116, v149, s[48:49]
	s_add_u32 s48, s48, 0x2000
	s_addc_u32 s49, s49, 0
	global_load_ushort v122, v149, s[48:49]
	s_add_u32 s48, s48, 0x2000
	s_addc_u32 s49, s49, 0
	global_load_ushort v118, v149, s[48:49]
	s_add_u32 s48, s48, 0x2000
	s_addc_u32 s49, s49, 0
	global_load_ushort v114, v149, s[48:49]
	s_add_u32 s48, s48, 0x2000
	s_addc_u32 s49, s49, 0
	global_load_ushort v112, v149, s[48:49]
	s_add_u32 s48, s48, 0x2000
	s_addc_u32 s49, s49, 0
	global_load_ushort v110, v149, s[48:49]
	s_add_u32 s48, s48, 0x2000
	s_addc_u32 s49, s49, 0
	global_load_ushort v108, v149, s[48:49]
	s_add_u32 s48, s48, 0x2000
	s_addc_u32 s49, s49, 0
	global_load_ushort v104, v149, s[48:49]
	s_add_u32 s48, s48, 0x2000
	s_addc_u32 s49, s49, 0
	global_load_ushort v100, v149, s[48:49]
	s_add_u32 s48, s48, 0x2000
	s_addc_u32 s49, s49, 0
	global_load_ushort v106, v149, s[48:49]
	s_add_u32 s48, s48, 0x2000
	s_addc_u32 s49, s49, 0
	global_load_ushort v102, v149, s[48:49]
	s_add_u32 s48, s48, 0x2000
	s_addc_u32 s49, s49, 0
	global_load_ushort v98, v149, s[48:49]
	s_add_u32 s48, s48, 0x2000
	s_addc_u32 s49, s49, 0
	global_load_ushort v96, v149, s[48:49]
	s_add_u32 s48, s48, 0x2000
	s_addc_u32 s49, s49, 0
	global_load_ushort v94, v149, s[48:49]
	s_add_u32 s48, s48, 0x2000
	s_addc_u32 s49, s49, 0
	global_load_ushort v92, v149, s[48:49]
	s_add_u32 s48, s48, 0x2000
	s_addc_u32 s49, s49, 0
	global_load_ushort v88, v149, s[48:49]
	s_add_u32 s48, s48, 0x2000
	s_addc_u32 s49, s49, 0
	global_load_ushort v84, v149, s[48:49]
	s_add_u32 s48, s48, 0x2000
	s_addc_u32 s49, s49, 0
	global_load_ushort v90, v149, s[48:49]
	s_add_u32 s48, s48, 0x2000
	s_addc_u32 s49, s49, 0
	global_load_ushort v86, v149, s[48:49]
	s_add_u32 s48, s48, 0x2000
	s_addc_u32 s49, s49, 0
	global_load_ushort v82, v149, s[48:49]
	s_add_u32 s48, s48, 0x2000
	s_addc_u32 s49, s49, 0
	global_load_ushort v80, v149, s[48:49]
	s_add_u32 s48, s48, 0x2000
	s_addc_u32 s49, s49, 0
	global_load_ushort v78, v149, s[48:49]
	s_add_u32 s48, s48, 0x2000
	s_addc_u32 s49, s49, 0
	global_load_ushort v76, v149, s[48:49]
	s_add_u32 s48, s48, 0x2000
	s_addc_u32 s49, s49, 0
	global_load_ushort v72, v149, s[48:49]
	s_add_u32 s48, s48, 0x2000
	s_addc_u32 s49, s49, 0
	global_load_ushort v60, v149, s[48:49]
	s_add_u32 s48, s48, 0x2000
	s_addc_u32 s49, s49, 0
	global_load_ushort v74, v149, s[48:49]
	s_add_u32 s48, s48, 0x2000
	s_addc_u32 s49, s49, 0
	global_load_ushort v62, v149, s[48:49]
	s_add_u32 s48, s48, 0x2000
	s_addc_u32 s49, s49, 0
	global_load_ushort v58, v149, s[48:49]
	s_add_u32 s48, s48, 0x2000
	s_addc_u32 s49, s49, 0
	global_load_ushort v56, v149, s[48:49]
	s_add_u32 s48, s48, 0x2000
	s_addc_u32 s49, s49, 0
	global_load_ushort v54, v149, s[48:49]
	s_add_u32 s48, s48, 0x2000
	s_addc_u32 s49, s49, 0
	global_load_ushort v52, v149, s[48:49]
	s_add_u32 s48, s48, 0x2000
	s_addc_u32 s49, s49, 0
	global_load_ushort v48, v149, s[48:49]
	s_add_u32 s48, s48, 0x2000
	s_addc_u32 s49, s49, 0
	global_load_ushort v44, v149, s[48:49]
	s_add_u32 s48, s48, 0x2000
	s_addc_u32 s49, s49, 0
	global_load_ushort v50, v149, s[48:49]
	s_add_u32 s48, s48, 0x2000
	s_addc_u32 s49, s49, 0
	global_load_ushort v46, v149, s[48:49]
	s_add_u32 s48, s48, 0x2000
	s_addc_u32 s49, s49, 0
	global_load_ushort v42, v149, s[48:49]
	s_add_u32 s48, s48, 0x2000
	s_addc_u32 s49, s49, 0
	global_load_ushort v40, v149, s[48:49]
	s_add_u32 s48, s48, 0x2000
	s_addc_u32 s49, s49, 0
	global_load_ushort v38, v149, s[48:49]
	s_add_u32 s48, s48, 0x2000
	s_addc_u32 s49, s49, 0
	global_load_ushort v36, v149, s[48:49]
	s_add_u32 s48, s48, 0x2000
	s_addc_u32 s49, s49, 0
	global_load_ushort v32, v149, s[48:49]
	s_add_u32 s48, s48, 0x2000
	s_addc_u32 s49, s49, 0
	global_load_ushort v28, v149, s[48:49]
	s_add_u32 s48, s48, 0x2000
	s_addc_u32 s49, s49, 0
	global_load_ushort v34, v149, s[48:49]
	s_add_u32 s48, s48, 0x2000
	s_addc_u32 s49, s49, 0
	global_load_ushort v30, v149, s[48:49]
	s_add_u32 s48, s48, 0x2000
	s_addc_u32 s49, s49, 0
	global_load_ushort v26, v149, s[48:49]
	s_add_u32 s48, s48, 0x2000
	s_addc_u32 s49, s49, 0
	global_load_ushort v24, v149, s[48:49]
	s_add_u32 s48, s48, 0x2000
	s_addc_u32 s49, s49, 0
	global_load_ushort v22, v149, s[48:49]
	s_add_u32 s48, s48, 0x2000
	s_addc_u32 s49, s49, 0
	global_load_ushort v20, v149, s[48:49]
	s_add_u32 s48, s48, 0x2000
	s_addc_u32 s49, s49, 0
	global_load_ushort v16, v149, s[48:49]
	s_add_u32 s48, s48, 0x2000
	s_addc_u32 s49, s49, 0
	global_load_ushort v12, v149, s[48:49]
	s_add_u32 s48, s48, 0x2000
	s_addc_u32 s49, s49, 0
	global_load_ushort v18, v149, s[48:49]
	s_add_u32 s48, s48, 0x2000
	s_addc_u32 s49, s49, 0
	global_load_ushort v14, v149, s[48:49]
	s_add_u32 s48, s48, 0x2000
	s_addc_u32 s49, s49, 0
	global_load_ushort v10, v149, s[48:49]
	s_add_u32 s48, s48, 0x2000
	s_addc_u32 s49, s49, 0
	global_load_ushort v8, v149, s[48:49]
	s_add_u32 s48, s48, 0x2000
	s_addc_u32 s49, s49, 0
	global_load_ushort v6, v149, s[48:49]
	s_add_u32 s48, s48, 0x2000
	s_addc_u32 s49, s49, 0
	global_load_ushort v4, v149, s[48:49]
	s_add_u32 s48, s48, 0x2000
	s_addc_u32 s49, s49, 0
	global_load_ushort v2, v149, s[48:49]
	s_add_u32 s48, s48, 0x2000
	s_addc_u32 s49, s49, 0
	global_load_ushort v0, v149, s[48:49]
	s_waitcnt vmcnt(0)
; __device__ __forceinline__ void sg_item(int l, int chunk, LAS unsigned char* lds, const bf16_t* UB, const bf16_t* V2T, bf16_t* YC1, const bf16_t* Wb,
;                                         const float* sg_ln_g, const float* sg_ln_b, const float* sg_b, int lane, int wave) {
;     ...
;             for (int j = 0; j < 8; ++j) v[cb + j] = __uint_as_float(raw[j] << 16);
;         }
; #pragma unroll
;         for (int c = 0; c < 64; ++c) { sum += v[c]; sq += v[c] * v[c]; }
	v_lshlrev_b32_e32 v132, 16, v132
	v_lshlrev_b32_e32 v133, 16, v133
	v_lshlrev_b32_e32 v130, 16, v130
	v_lshlrev_b32_e32 v128, 16, v128
	v_lshlrev_b32_e32 v126, 16, v126
	v_lshlrev_b32_e32 v124, 16, v124
	v_lshlrev_b32_e32 v120, 16, v120
	v_lshlrev_b32_e32 v116, 16, v116
	v_lshlrev_b32_e32 v122, 16, v122
	v_lshlrev_b32_e32 v118, 16, v118
	v_lshlrev_b32_e32 v114, 16, v114
	v_lshlrev_b32_e32 v112, 16, v112
	v_lshlrev_b32_e32 v110, 16, v110
	v_lshlrev_b32_e32 v108, 16, v108
	v_lshlrev_b32_e32 v104, 16, v104
	v_lshlrev_b32_e32 v100, 16, v100
	v_lshlrev_b32_e32 v106, 16, v106
	v_lshlrev_b32_e32 v102, 16, v102
	v_lshlrev_b32_e32 v98, 16, v98
	v_lshlrev_b32_e32 v96, 16, v96
	v_lshlrev_b32_e32 v94, 16, v94
	v_lshlrev_b32_e32 v92, 16, v92
	v_lshlrev_b32_e32 v88, 16, v88
	v_lshlrev_b32_e32 v84, 16, v84
	v_lshlrev_b32_e32 v90, 16, v90
	v_lshlrev_b32_e32 v86, 16, v86
	v_lshlrev_b32_e32 v82, 16, v82
	v_lshlrev_b32_e32 v80, 16, v80
	v_lshlrev_b32_e32 v78, 16, v78
	v_lshlrev_b32_e32 v76, 16, v76
	v_lshlrev_b32_e32 v72, 16, v72
	v_lshlrev_b32_e32 v60, 16, v60
	v_lshlrev_b32_e32 v74, 16, v74
	v_lshlrev_b32_e32 v62, 16, v62
	v_lshlrev_b32_e32 v58, 16, v58
	v_lshlrev_b32_e32 v56, 16, v56
	v_lshlrev_b32_e32 v54, 16, v54
	v_lshlrev_b32_e32 v52, 16, v52
	v_lshlrev_b32_e32 v48, 16, v48
	v_lshlrev_b32_e32 v44, 16, v44
	v_lshlrev_b32_e32 v50, 16, v50
	v_lshlrev_b32_e32 v46, 16, v46
	v_lshlrev_b32_e32 v42, 16, v42
	v_lshlrev_b32_e32 v40, 16, v40
	v_lshlrev_b32_e32 v38, 16, v38
	v_lshlrev_b32_e32 v36, 16, v36
	v_lshlrev_b32_e32 v32, 16, v32
	v_lshlrev_b32_e32 v28, 16, v28
	v_lshlrev_b32_e32 v34, 16, v34
	v_lshlrev_b32_e32 v30, 16, v30
	v_lshlrev_b32_e32 v26, 16, v26
	v_lshlrev_b32_e32 v24, 16, v24
	v_lshlrev_b32_e32 v22, 16, v22
	v_lshlrev_b32_e32 v20, 16, v20
	v_lshlrev_b32_e32 v16, 16, v16
	v_lshlrev_b32_e32 v12, 16, v12
	v_lshlrev_b32_e32 v18, 16, v18
	v_lshlrev_b32_e32 v14, 16, v14
	v_lshlrev_b32_e32 v10, 16, v10
	v_lshlrev_b32_e32 v8, 16, v8
	v_lshlrev_b32_e32 v6, 16, v6
	v_lshlrev_b32_e32 v4, 16, v4
	v_lshlrev_b32_e32 v2, 16, v2
	v_lshlrev_b32_e32 v0, 16, v0
	v_mul_f32_e32 v221, v132, v132
	v_fmac_f32_e32 v221, v133, v133
	v_add_f32_e32 v220, v132, v133
	v_mul_f32_e32 v131, v130, v130
	v_pk_add_f32 v[220:221], v[220:221], v[130:131]
	v_mul_f32_e32 v129, v128, v128
	v_pk_add_f32 v[220:221], v[220:221], v[128:129]
	v_mul_f32_e32 v127, v126, v126
	v_pk_add_f32 v[220:221], v[220:221], v[126:127]
	v_mul_f32_e32 v125, v124, v124
	v_pk_add_f32 v[220:221], v[220:221], v[124:125]
	v_mul_f32_e32 v121, v120, v120
	v_pk_add_f32 v[220:221], v[220:221], v[120:121]
	v_mul_f32_e32 v117, v116, v116
	v_pk_add_f32 v[220:221], v[220:221], v[116:117]
	v_mul_f32_e32 v123, v122, v122
	v_pk_add_f32 v[220:221], v[220:221], v[122:123]
	v_mul_f32_e32 v119, v118, v118
	v_pk_add_f32 v[220:221], v[220:221], v[118:119]
	v_mul_f32_e32 v115, v114, v114
	v_pk_add_f32 v[220:221], v[220:221], v[114:115]
	v_mul_f32_e32 v113, v112, v112
	v_pk_add_f32 v[220:221], v[220:221], v[112:113]
	v_mul_f32_e32 v111, v110, v110
	v_pk_add_f32 v[220:221], v[220:221], v[110:111]
	v_mul_f32_e32 v109, v108, v108
	v_pk_add_f32 v[220:221], v[220:221], v[108:109]
	v_mul_f32_e32 v105, v104, v104
	v_pk_add_f32 v[220:221], v[220:221], v[104:105]
	v_mul_f32_e32 v101, v100, v100
	v_pk_add_f32 v[220:221], v[220:221], v[100:101]
	v_mul_f32_e32 v107, v106, v106
	v_pk_add_f32 v[220:221], v[220:221], v[106:107]
	v_mul_f32_e32 v103, v102, v102
	v_pk_add_f32 v[220:221], v[220:221], v[102:103]
	v_mul_f32_e32 v99, v98, v98
	v_pk_add_f32 v[220:221], v[220:221], v[98:99]
	v_mul_f32_e32 v97, v96, v96
	v_pk_add_f32 v[220:221], v[220:221], v[96:97]
	v_mul_f32_e32 v95, v94, v94
	v_pk_add_f32 v[220:221], v[220:221], v[94:95]
	v_mul_f32_e32 v93, v92, v92
	v_pk_add_f32 v[220:221], v[220:221], v[92:93]
	v_mul_f32_e32 v89, v88, v88
	v_pk_add_f32 v[220:221], v[220:221], v[88:89]
	v_mul_f32_e32 v85, v84, v84
	v_pk_add_f32 v[220:221], v[220:221], v[84:85]
	v_mul_f32_e32 v91, v90, v90
	v_pk_add_f32 v[220:221], v[220:221], v[90:91]
	v_mul_f32_e32 v87, v86, v86
	v_pk_add_f32 v[220:221], v[220:221], v[86:87]
	v_mul_f32_e32 v83, v82, v82
	v_pk_add_f32 v[220:221], v[220:221], v[82:83]
	v_mul_f32_e32 v81, v80, v80
	v_pk_add_f32 v[220:221], v[220:221], v[80:81]
	v_mul_f32_e32 v79, v78, v78
	v_pk_add_f32 v[220:221], v[220:221], v[78:79]
	v_mul_f32_e32 v77, v76, v76
	v_pk_add_f32 v[220:221], v[220:221], v[76:77]
	v_mul_f32_e32 v73, v72, v72
	v_pk_add_f32 v[220:221], v[220:221], v[72:73]
	v_mul_f32_e32 v61, v60, v60
	v_pk_add_f32 v[220:221], v[220:221], v[60:61]
	v_mul_f32_e32 v75, v74, v74
	v_pk_add_f32 v[220:221], v[220:221], v[74:75]
	v_mul_f32_e32 v63, v62, v62
	v_pk_add_f32 v[220:221], v[220:221], v[62:63]
	v_mul_f32_e32 v59, v58, v58
	v_pk_add_f32 v[220:221], v[220:221], v[58:59]
	v_mul_f32_e32 v57, v56, v56
	v_pk_add_f32 v[220:221], v[220:221], v[56:57]
	v_mul_f32_e32 v55, v54, v54
	v_pk_add_f32 v[220:221], v[220:221], v[54:55]
	v_mul_f32_e32 v53, v52, v52
	v_pk_add_f32 v[220:221], v[220:221], v[52:53]
	v_mul_f32_e32 v49, v48, v48
	v_pk_add_f32 v[220:221], v[220:221], v[48:49]
	v_mul_f32_e32 v45, v44, v44
	v_pk_add_f32 v[220:221], v[220:221], v[44:45]
	v_mul_f32_e32 v51, v50, v50
	v_pk_add_f32 v[220:221], v[220:221], v[50:51]
	v_mul_f32_e32 v47, v46, v46
	v_pk_add_f32 v[220:221], v[220:221], v[46:47]
	v_mul_f32_e32 v43, v42, v42
	v_pk_add_f32 v[220:221], v[220:221], v[42:43]
	v_mul_f32_e32 v41, v40, v40
	v_pk_add_f32 v[220:221], v[220:221], v[40:41]
	v_mul_f32_e32 v39, v38, v38
	v_pk_add_f32 v[220:221], v[220:221], v[38:39]
	v_mul_f32_e32 v37, v36, v36
	v_pk_add_f32 v[220:221], v[220:221], v[36:37]
	v_mul_f32_e32 v33, v32, v32
; __device__ __forceinline__ bf16_t f2bf(float f) { return (bf16_t)(cvt_pk_bf16(f, f) & 0xffffu); }
; __device__ __forceinline__ float ln_eps_s() { float e = LN_EPS; asm volatile("" : "+s"(e)); return e; }
; __device__ __forceinline__ void sg_item(int l, int chunk, LAS unsigned char* lds, const bf16_t* UB, const bf16_t* V2T, bf16_t* YC1, const bf16_t* Wb,
;                                         const float* sg_ln_g, const float* sg_ln_b, const float* sg_b, int lane, int wave) {
;     ...
;         for (int c = 0; c < 64; ++c) { sum += v[c]; sq += v[c] * v[c]; }
;         part[(cq * 128 + s) * 2] = sum; part[(cq * 128 + s) * 2 + 1] = sq;
;         const float gl = sg_ln_g[l * BW + 64 * cq + lane], bl = sg_ln_b[l * BW + 64 * cq + lane];
;         __syncthreads();
;         float ts = 0.f, tq = 0.f;
; #pragma unroll
;         for (int k = 0; k < 4; ++k) { ts += part[(k * 128 + s) * 2]; tq += part[(k * 128 + s) * 2 + 1]; }
;         const float mean = ts * (1.f / BW), var = fmaxf(tq * (1.f / BW) - mean * mean, 0.f), rstd = __builtin_amdgcn_rsqf(var + ln_eps_s());
; #pragma unroll
;         for (int c = 0; c < 64; ++c) {
;             const float gc = __uint_as_float(__builtin_amdgcn_readlane(__float_as_uint(gl), c)), bc = __uint_as_float(__builtin_amdgcn_readlane(__float_as_uint(bl), c));
;             vT[(64 * cq + c) * VS + s] = f2bf((v[c] - mean) * rstd * gc + bc);
	v_pk_add_f32 v[220:221], v[220:221], v[32:33]
	v_mul_f32_e32 v29, v28, v28
	v_pk_add_f32 v[220:221], v[220:221], v[28:29]
	v_mul_f32_e32 v35, v34, v34
	v_pk_add_f32 v[220:221], v[220:221], v[34:35]
	v_mul_f32_e32 v31, v30, v30
	v_pk_add_f32 v[220:221], v[220:221], v[30:31]
	v_mul_f32_e32 v27, v26, v26
	v_pk_add_f32 v[220:221], v[220:221], v[26:27]
	v_mul_f32_e32 v25, v24, v24
	v_pk_add_f32 v[220:221], v[220:221], v[24:25]
	v_mul_f32_e32 v23, v22, v22
	v_pk_add_f32 v[220:221], v[220:221], v[22:23]
	v_mul_f32_e32 v21, v20, v20
	v_pk_add_f32 v[220:221], v[220:221], v[20:21]
	v_mul_f32_e32 v17, v16, v16
	v_pk_add_f32 v[220:221], v[220:221], v[16:17]
	v_mul_f32_e32 v13, v12, v12
	v_pk_add_f32 v[220:221], v[220:221], v[12:13]
	v_mul_f32_e32 v19, v18, v18
	v_pk_add_f32 v[220:221], v[220:221], v[18:19]
	v_mul_f32_e32 v15, v14, v14
	v_pk_add_f32 v[220:221], v[220:221], v[14:15]
	v_mul_f32_e32 v11, v10, v10
	v_pk_add_f32 v[220:221], v[220:221], v[10:11]
	v_mul_f32_e32 v9, v8, v8
	v_pk_add_f32 v[220:221], v[220:221], v[8:9]
	v_mul_f32_e32 v7, v6, v6
	v_pk_add_f32 v[220:221], v[220:221], v[6:7]
	v_mul_f32_e32 v5, v4, v4
	v_pk_add_f32 v[220:221], v[220:221], v[4:5]
	v_mul_f32_e32 v3, v2, v2
	v_pk_add_f32 v[220:221], v[220:221], v[2:3]
	v_mul_f32_e32 v1, v0, v0
	v_pk_add_f32 v[220:221], v[220:221], v[0:1]
	s_mov_b32 s0, 0x3b800000
	ds_write_b64 v150, v[220:221]
	global_load_dword v1, v[64:65], off
	global_load_dword v3, v[66:67], off
	s_waitcnt lgkmcnt(0)
	s_barrier
	ds_read2st64_b64 v[220:223], v151 offset1:2
	s_add_u32 s48, s4, s80
	s_addc_u32 s49, s5, s81
	s_mov_b32 s12, 0xb400000
	s_waitcnt lgkmcnt(0)
	v_add_f32_e32 v5, 0, v220
	v_add_f32_e32 v7, 0, v221
	v_add_f32_e32 v5, v5, v222
	v_add_f32_e32 v7, v7, v223
	ds_read2st64_b64 v[220:223], v151 offset0:4 offset1:6
	s_waitcnt lgkmcnt(0)
	v_add_f32_e32 v5, v5, v220
	v_add_f32_e32 v5, v5, v222
	v_add_f32_e32 v7, v7, v221
	v_mul_f32_e32 v9, 0x3b800000, v5
	v_add_f32_e32 v7, v7, v223
	v_mul_f32_e32 v9, v9, v9
	v_fma_f32 v7, v7, s0, -v9
	v_max_f32_e32 v7, 0, v7
	s_mov_b32 s0, 0x3727c5ac
	v_fmac_f32_e32 v132, 0xbb800000, v5
	v_add_f32_e32 v7, s0, v7
	v_rsq_f32_e32 v7, v7
	v_fmac_f32_e32 v133, 0xbb800000, v5
	v_fmac_f32_e32 v130, 0xbb800000, v5
	v_fmac_f32_e32 v128, 0xbb800000, v5
	v_mul_f32_e32 v9, v132, v7
	v_fmac_f32_e32 v126, 0xbb800000, v5
	v_fmac_f32_e32 v124, 0xbb800000, v5
	v_fmac_f32_e32 v120, 0xbb800000, v5
	v_fmac_f32_e32 v116, 0xbb800000, v5
	v_fmac_f32_e32 v122, 0xbb800000, v5
	v_fmac_f32_e32 v118, 0xbb800000, v5
	v_fmac_f32_e32 v114, 0xbb800000, v5
	v_fmac_f32_e32 v112, 0xbb800000, v5
	v_fmac_f32_e32 v110, 0xbb800000, v5
	v_fmac_f32_e32 v108, 0xbb800000, v5
	v_fmac_f32_e32 v104, 0xbb800000, v5
	v_fmac_f32_e32 v100, 0xbb800000, v5
	v_fmac_f32_e32 v106, 0xbb800000, v5
	v_fmac_f32_e32 v102, 0xbb800000, v5
	v_fmac_f32_e32 v98, 0xbb800000, v5
	v_fmac_f32_e32 v96, 0xbb800000, v5
	v_fmac_f32_e32 v94, 0xbb800000, v5
	v_fmac_f32_e32 v92, 0xbb800000, v5
	v_fmac_f32_e32 v88, 0xbb800000, v5
	v_fmac_f32_e32 v84, 0xbb800000, v5
	v_fmac_f32_e32 v90, 0xbb800000, v5
	v_fmac_f32_e32 v86, 0xbb800000, v5
	v_fmac_f32_e32 v82, 0xbb800000, v5
	v_fmac_f32_e32 v80, 0xbb800000, v5
	v_fmac_f32_e32 v78, 0xbb800000, v5
	v_fmac_f32_e32 v76, 0xbb800000, v5
	v_fmac_f32_e32 v72, 0xbb800000, v5
	v_fmac_f32_e32 v60, 0xbb800000, v5
	v_fmac_f32_e32 v74, 0xbb800000, v5
	v_fmac_f32_e32 v62, 0xbb800000, v5
	v_fmac_f32_e32 v58, 0xbb800000, v5
	v_fmac_f32_e32 v56, 0xbb800000, v5
	v_fmac_f32_e32 v54, 0xbb800000, v5
	v_fmac_f32_e32 v52, 0xbb800000, v5
	v_fmac_f32_e32 v48, 0xbb800000, v5
	v_fmac_f32_e32 v44, 0xbb800000, v5
	v_fmac_f32_e32 v50, 0xbb800000, v5
	v_fmac_f32_e32 v46, 0xbb800000, v5
	v_fmac_f32_e32 v42, 0xbb800000, v5
	v_fmac_f32_e32 v40, 0xbb800000, v5
	v_fmac_f32_e32 v38, 0xbb800000, v5
	v_fmac_f32_e32 v36, 0xbb800000, v5
	v_fmac_f32_e32 v32, 0xbb800000, v5
	v_fmac_f32_e32 v28, 0xbb800000, v5
	s_waitcnt vmcnt(1)
	v_readlane_b32 s0, v1, 0
	s_waitcnt vmcnt(0)
	v_readlane_b32 s1, v3, 0
	v_fmac_f32_e32 v34, 0xbb800000, v5
	v_fmac_f32_e32 v30, 0xbb800000, v5
	v_mov_b32_e32 v11, s1
	v_fmac_f32_e32 v11, s0, v9
	v_cvt_pk_bf16_f32 v9, v11, v11
	v_readlane_b32 s1, v3, 1
	ds_write_b16 v202, v9
	v_readlane_b32 s0, v1, 1
	v_mul_f32_e32 v9, v133, v7
	v_mov_b32_e32 v11, s1
	v_fmac_f32_e32 v11, s0, v9
	v_cvt_pk_bf16_f32 v9, v11, v11
	v_readlane_b32 s1, v3, 2
	ds_write_b16 v202, v9 offset:272
	v_readlane_b32 s0, v1, 2
	v_mul_f32_e32 v9, v130, v7
	v_mov_b32_e32 v11, s1
	v_fmac_f32_e32 v11, s0, v9
	v_cvt_pk_bf16_f32 v9, v11, v11
	v_readlane_b32 s1, v3, 3
	ds_write_b16 v202, v9 offset:544
	v_readlane_b32 s0, v1, 3
	v_mul_f32_e32 v9, v128, v7
	v_mov_b32_e32 v11, s1
	v_fmac_f32_e32 v11, s0, v9
	v_cvt_pk_bf16_f32 v9, v11, v11
	v_readlane_b32 s1, v3, 4
	ds_write_b16 v202, v9 offset:816
	v_readlane_b32 s0, v1, 4
	v_mul_f32_e32 v9, v126, v7
	v_mov_b32_e32 v11, s1
	v_fmac_f32_e32 v11, s0, v9
	v_cvt_pk_bf16_f32 v9, v11, v11
	v_readlane_b32 s1, v3, 5
	ds_write_b16 v202, v9 offset:1088
	v_readlane_b32 s0, v1, 5
	v_mul_f32_e32 v9, v124, v7
	v_mov_b32_e32 v11, s1
	v_fmac_f32_e32 v11, s0, v9
	v_cvt_pk_bf16_f32 v9, v11, v11
	v_readlane_b32 s1, v3, 6
	ds_write_b16 v202, v9 offset:1360
	v_readlane_b32 s0, v1, 6
	v_mul_f32_e32 v9, v120, v7
	v_mov_b32_e32 v11, s1
	v_fmac_f32_e32 v11, s0, v9
	v_cvt_pk_bf16_f32 v9, v11, v11
	v_readlane_b32 s1, v3, 7
	ds_write_b16 v202, v9 offset:1632
	v_readlane_b32 s0, v1, 7
	v_mul_f32_e32 v9, v116, v7
	v_mov_b32_e32 v11, s1
	v_fmac_f32_e32 v11, s0, v9
	v_cvt_pk_bf16_f32 v9, v11, v11
	v_readlane_b32 s1, v3, 8
	ds_write_b16 v202, v9 offset:1904
	v_readlane_b32 s0, v1, 8
	v_mul_f32_e32 v9, v122, v7
	v_mov_b32_e32 v11, s1
; __device__ __forceinline__ bf16_t f2bf(float f) { return (bf16_t)(cvt_pk_bf16(f, f) & 0xffffu); }
; __device__ __forceinline__ void sg_item(int l, int chunk, LAS unsigned char* lds, const bf16_t* UB, const bf16_t* V2T, bf16_t* YC1, const bf16_t* Wb,
;                                         const float* sg_ln_g, const float* sg_ln_b, const float* sg_b, int lane, int wave) {
;     ...
; #pragma unroll
;         for (int c = 0; c < 64; ++c) {
;             const float gc = __uint_as_float(__builtin_amdgcn_readlane(__float_as_uint(gl), c)), bc = __uint_as_float(__builtin_amdgcn_readlane(__float_as_uint(bl), c));
;             vT[(64 * cq + c) * VS + s] = f2bf((v[c] - mean) * rstd * gc + bc);
;         }
	v_fmac_f32_e32 v11, s0, v9
	v_cvt_pk_bf16_f32 v9, v11, v11
	v_readlane_b32 s1, v3, 9
	ds_write_b16 v202, v9 offset:2176
	v_readlane_b32 s0, v1, 9
	v_mul_f32_e32 v9, v118, v7
	v_mov_b32_e32 v11, s1
	v_fmac_f32_e32 v11, s0, v9
	v_cvt_pk_bf16_f32 v9, v11, v11
	v_readlane_b32 s1, v3, 10
	ds_write_b16 v202, v9 offset:2448
	v_readlane_b32 s0, v1, 10
	v_mul_f32_e32 v9, v114, v7
	v_mov_b32_e32 v11, s1
	v_fmac_f32_e32 v11, s0, v9
	v_cvt_pk_bf16_f32 v9, v11, v11
	v_readlane_b32 s1, v3, 11
	ds_write_b16 v202, v9 offset:2720
	v_readlane_b32 s0, v1, 11
	v_mul_f32_e32 v9, v112, v7
	v_mov_b32_e32 v11, s1
	v_fmac_f32_e32 v11, s0, v9
	v_cvt_pk_bf16_f32 v9, v11, v11
	v_readlane_b32 s1, v3, 12
	ds_write_b16 v202, v9 offset:2992
	v_readlane_b32 s0, v1, 12
	v_mul_f32_e32 v9, v110, v7
	v_mov_b32_e32 v11, s1
	v_fmac_f32_e32 v11, s0, v9
	v_cvt_pk_bf16_f32 v9, v11, v11
	v_readlane_b32 s1, v3, 13
	ds_write_b16 v202, v9 offset:3264
	v_readlane_b32 s0, v1, 13
	v_mul_f32_e32 v9, v108, v7
	v_mov_b32_e32 v11, s1
	v_fmac_f32_e32 v11, s0, v9
	v_cvt_pk_bf16_f32 v9, v11, v11
	v_readlane_b32 s1, v3, 14
	ds_write_b16 v202, v9 offset:3536
	v_readlane_b32 s0, v1, 14
	v_mul_f32_e32 v9, v104, v7
	v_mov_b32_e32 v11, s1
	v_fmac_f32_e32 v11, s0, v9
	v_cvt_pk_bf16_f32 v9, v11, v11
	v_readlane_b32 s1, v3, 15
	ds_write_b16 v202, v9 offset:3808
	v_readlane_b32 s0, v1, 15
	v_mul_f32_e32 v9, v100, v7
	v_mov_b32_e32 v11, s1
	v_fmac_f32_e32 v11, s0, v9
	v_cvt_pk_bf16_f32 v9, v11, v11
	v_readlane_b32 s1, v3, 16
	ds_write_b16 v202, v9 offset:4080
	v_readlane_b32 s0, v1, 16
	v_mul_f32_e32 v9, v106, v7
	v_mov_b32_e32 v11, s1
	v_fmac_f32_e32 v11, s0, v9
	v_cvt_pk_bf16_f32 v9, v11, v11
	v_readlane_b32 s1, v3, 17
	ds_write_b16 v202, v9 offset:4352
	v_readlane_b32 s0, v1, 17
	v_mul_f32_e32 v9, v102, v7
	v_mov_b32_e32 v11, s1
	v_fmac_f32_e32 v11, s0, v9
	v_cvt_pk_bf16_f32 v9, v11, v11
	v_readlane_b32 s1, v3, 18
	ds_write_b16 v202, v9 offset:4624
	v_readlane_b32 s0, v1, 18
	v_mul_f32_e32 v9, v98, v7
	v_mov_b32_e32 v11, s1
	v_fmac_f32_e32 v11, s0, v9
	v_cvt_pk_bf16_f32 v9, v11, v11
	v_readlane_b32 s1, v3, 19
	ds_write_b16 v202, v9 offset:4896
	v_readlane_b32 s0, v1, 19
	v_mul_f32_e32 v9, v96, v7
	v_mov_b32_e32 v11, s1
	v_fmac_f32_e32 v11, s0, v9
	v_cvt_pk_bf16_f32 v9, v11, v11
	v_readlane_b32 s1, v3, 20
	ds_write_b16 v202, v9 offset:5168
	v_readlane_b32 s0, v1, 20
	v_mul_f32_e32 v9, v94, v7
	v_mov_b32_e32 v11, s1
	v_fmac_f32_e32 v11, s0, v9
	v_cvt_pk_bf16_f32 v9, v11, v11
	v_readlane_b32 s1, v3, 21
	ds_write_b16 v202, v9 offset:5440
	v_readlane_b32 s0, v1, 21
	v_mul_f32_e32 v9, v92, v7
	v_mov_b32_e32 v11, s1
	v_fmac_f32_e32 v11, s0, v9
	v_cvt_pk_bf16_f32 v9, v11, v11
	v_readlane_b32 s1, v3, 22
	ds_write_b16 v202, v9 offset:5712
	v_readlane_b32 s0, v1, 22
	v_mul_f32_e32 v9, v88, v7
	v_mov_b32_e32 v11, s1
	v_fmac_f32_e32 v11, s0, v9
	v_cvt_pk_bf16_f32 v9, v11, v11
	v_readlane_b32 s1, v3, 23
	ds_write_b16 v202, v9 offset:5984
	v_readlane_b32 s0, v1, 23
	v_mul_f32_e32 v9, v84, v7
	v_mov_b32_e32 v11, s1
	v_fmac_f32_e32 v11, s0, v9
	v_cvt_pk_bf16_f32 v9, v11, v11
	v_readlane_b32 s1, v3, 24
	ds_write_b16 v202, v9 offset:6256
	v_readlane_b32 s0, v1, 24
	v_mul_f32_e32 v9, v90, v7
	v_mov_b32_e32 v11, s1
	v_fmac_f32_e32 v11, s0, v9
	v_cvt_pk_bf16_f32 v9, v11, v11
	v_readlane_b32 s1, v3, 25
	ds_write_b16 v202, v9 offset:6528
	v_readlane_b32 s0, v1, 25
	v_mul_f32_e32 v9, v86, v7
	v_mov_b32_e32 v11, s1
	v_fmac_f32_e32 v11, s0, v9
	v_cvt_pk_bf16_f32 v9, v11, v11
	v_readlane_b32 s1, v3, 26
	ds_write_b16 v202, v9 offset:6800
	v_readlane_b32 s0, v1, 26
	v_mul_f32_e32 v9, v82, v7
	v_mov_b32_e32 v11, s1
	v_fmac_f32_e32 v11, s0, v9
	v_cvt_pk_bf16_f32 v9, v11, v11
	v_readlane_b32 s1, v3, 27
	ds_write_b16 v202, v9 offset:7072
	v_readlane_b32 s0, v1, 27
	v_mul_f32_e32 v9, v80, v7
	v_mov_b32_e32 v11, s1
	v_fmac_f32_e32 v11, s0, v9
	v_cvt_pk_bf16_f32 v9, v11, v11
	v_readlane_b32 s1, v3, 28
	ds_write_b16 v202, v9 offset:7344
	v_readlane_b32 s0, v1, 28
	v_mul_f32_e32 v9, v78, v7
	v_mov_b32_e32 v11, s1
	v_fmac_f32_e32 v11, s0, v9
	v_cvt_pk_bf16_f32 v9, v11, v11
	v_readlane_b32 s1, v3, 29
	ds_write_b16 v202, v9 offset:7616
	v_readlane_b32 s0, v1, 29
	v_mul_f32_e32 v9, v76, v7
	v_mov_b32_e32 v11, s1
	v_fmac_f32_e32 v11, s0, v9
	v_cvt_pk_bf16_f32 v9, v11, v11
	v_readlane_b32 s1, v3, 30
	ds_write_b16 v202, v9 offset:7888
	v_readlane_b32 s0, v1, 30
	v_mul_f32_e32 v9, v72, v7
	v_mov_b32_e32 v11, s1
	v_fmac_f32_e32 v11, s0, v9
	v_cvt_pk_bf16_f32 v9, v11, v11
	v_readlane_b32 s1, v3, 31
	ds_write_b16 v202, v9 offset:8160
	v_readlane_b32 s0, v1, 31
	v_mul_f32_e32 v9, v60, v7
	v_mov_b32_e32 v11, s1
	v_fmac_f32_e32 v11, s0, v9
	v_cvt_pk_bf16_f32 v9, v11, v11
	v_readlane_b32 s1, v3, 32
	ds_write_b16 v202, v9 offset:8432
	v_readlane_b32 s0, v1, 32
	v_mul_f32_e32 v9, v74, v7
	v_mov_b32_e32 v11, s1
	v_fmac_f32_e32 v11, s0, v9
	v_cvt_pk_bf16_f32 v9, v11, v11
	v_readlane_b32 s1, v3, 33
	ds_write_b16 v202, v9 offset:8704
	v_readlane_b32 s0, v1, 33
	v_mul_f32_e32 v9, v62, v7
	v_mov_b32_e32 v11, s1
	v_fmac_f32_e32 v11, s0, v9
	v_cvt_pk_bf16_f32 v9, v11, v11
	v_readlane_b32 s1, v3, 34
	ds_write_b16 v202, v9 offset:8976
	v_readlane_b32 s0, v1, 34
	v_mul_f32_e32 v9, v58, v7
	v_mov_b32_e32 v11, s1
	v_fmac_f32_e32 v11, s0, v9
	v_cvt_pk_bf16_f32 v9, v11, v11
	v_readlane_b32 s1, v3, 35
	ds_write_b16 v202, v9 offset:9248
	v_readlane_b32 s0, v1, 35
	v_mul_f32_e32 v9, v56, v7
	v_mov_b32_e32 v11, s1
	v_fmac_f32_e32 v11, s0, v9
	v_cvt_pk_bf16_f32 v9, v11, v11
	v_readlane_b32 s1, v3, 36
	ds_write_b16 v202, v9 offset:9520
	v_readlane_b32 s0, v1, 36
	v_mul_f32_e32 v9, v54, v7
	v_mov_b32_e32 v11, s1
	v_fmac_f32_e32 v11, s0, v9
	v_cvt_pk_bf16_f32 v9, v11, v11
; __device__ __forceinline__ bf16_t f2bf(float f) { return (bf16_t)(cvt_pk_bf16(f, f) & 0xffffu); }
; __device__ __forceinline__ void sg_item(int l, int chunk, LAS unsigned char* lds, const bf16_t* UB, const bf16_t* V2T, bf16_t* YC1, const bf16_t* Wb,
;                                         const float* sg_ln_g, const float* sg_ln_b, const float* sg_b, int lane, int wave) {
;     ...
; #pragma unroll
;         for (int c = 0; c < 64; ++c) {
;             const float gc = __uint_as_float(__builtin_amdgcn_readlane(__float_as_uint(gl), c)), bc = __uint_as_float(__builtin_amdgcn_readlane(__float_as_uint(bl), c));
;             vT[(64 * cq + c) * VS + s] = f2bf((v[c] - mean) * rstd * gc + bc);
;         }
;     }
;     __syncthreads();
	v_readlane_b32 s1, v3, 37
	ds_write_b16 v202, v9 offset:9792
	v_readlane_b32 s0, v1, 37
	v_mul_f32_e32 v9, v52, v7
	v_mov_b32_e32 v11, s1
	v_fmac_f32_e32 v11, s0, v9
	v_cvt_pk_bf16_f32 v9, v11, v11
	v_readlane_b32 s1, v3, 38
	ds_write_b16 v202, v9 offset:10064
	v_readlane_b32 s0, v1, 38
	v_mul_f32_e32 v9, v48, v7
	v_mov_b32_e32 v11, s1
	v_fmac_f32_e32 v11, s0, v9
	v_cvt_pk_bf16_f32 v9, v11, v11
	v_readlane_b32 s1, v3, 39
	ds_write_b16 v202, v9 offset:10336
	v_readlane_b32 s0, v1, 39
	v_mul_f32_e32 v9, v44, v7
	v_mov_b32_e32 v11, s1
	v_fmac_f32_e32 v11, s0, v9
	v_cvt_pk_bf16_f32 v9, v11, v11
	v_readlane_b32 s1, v3, 40
	ds_write_b16 v202, v9 offset:10608
	v_readlane_b32 s0, v1, 40
	v_mul_f32_e32 v9, v50, v7
	v_mov_b32_e32 v11, s1
	v_fmac_f32_e32 v11, s0, v9
	v_cvt_pk_bf16_f32 v9, v11, v11
	v_readlane_b32 s1, v3, 41
	ds_write_b16 v202, v9 offset:10880
	v_readlane_b32 s0, v1, 41
	v_mul_f32_e32 v9, v46, v7
	v_mov_b32_e32 v11, s1
	v_fmac_f32_e32 v11, s0, v9
	v_cvt_pk_bf16_f32 v9, v11, v11
	v_readlane_b32 s1, v3, 42
	ds_write_b16 v202, v9 offset:11152
	v_readlane_b32 s0, v1, 42
	v_mul_f32_e32 v9, v42, v7
	v_mov_b32_e32 v11, s1
	v_fmac_f32_e32 v11, s0, v9
	v_cvt_pk_bf16_f32 v9, v11, v11
	v_readlane_b32 s1, v3, 43
	ds_write_b16 v202, v9 offset:11424
	v_readlane_b32 s0, v1, 43
	v_mul_f32_e32 v9, v40, v7
	v_mov_b32_e32 v11, s1
	v_fmac_f32_e32 v11, s0, v9
	v_cvt_pk_bf16_f32 v9, v11, v11
	v_readlane_b32 s1, v3, 44
	ds_write_b16 v202, v9 offset:11696
	v_readlane_b32 s0, v1, 44
	v_mul_f32_e32 v9, v38, v7
	v_mov_b32_e32 v11, s1
	v_fmac_f32_e32 v11, s0, v9
	v_cvt_pk_bf16_f32 v9, v11, v11
	v_readlane_b32 s1, v3, 45
	ds_write_b16 v202, v9 offset:11968
	v_readlane_b32 s0, v1, 45
	v_mul_f32_e32 v9, v36, v7
	v_mov_b32_e32 v11, s1
	v_fmac_f32_e32 v11, s0, v9
	v_cvt_pk_bf16_f32 v9, v11, v11
	v_readlane_b32 s1, v3, 46
	ds_write_b16 v202, v9 offset:12240
	v_readlane_b32 s0, v1, 46
	v_mul_f32_e32 v9, v32, v7
	v_mov_b32_e32 v11, s1
	v_fmac_f32_e32 v11, s0, v9
	v_cvt_pk_bf16_f32 v9, v11, v11
	v_readlane_b32 s1, v3, 47
	ds_write_b16 v202, v9 offset:12512
	v_readlane_b32 s0, v1, 47
	v_mul_f32_e32 v9, v28, v7
	v_mov_b32_e32 v11, s1
	v_fmac_f32_e32 v11, s0, v9
	v_cvt_pk_bf16_f32 v9, v11, v11
	v_readlane_b32 s1, v3, 48
	ds_write_b16 v202, v9 offset:12784
	v_readlane_b32 s0, v1, 48
	v_mul_f32_e32 v9, v34, v7
	v_mov_b32_e32 v11, s1
	v_fmac_f32_e32 v11, s0, v9
	v_cvt_pk_bf16_f32 v9, v11, v11
	v_readlane_b32 s1, v3, 49
	ds_write_b16 v202, v9 offset:13056
	v_readlane_b32 s0, v1, 49
	v_mul_f32_e32 v9, v30, v7
	v_mov_b32_e32 v11, s1
	v_fmac_f32_e32 v11, s0, v9
	v_cvt_pk_bf16_f32 v9, v11, v11
	v_readlane_b32 s1, v3, 50
	v_fmac_f32_e32 v26, 0xbb800000, v5
	ds_write_b16 v202, v9 offset:13328
	v_readlane_b32 s0, v1, 50
	v_mul_f32_e32 v9, v26, v7
	v_mov_b32_e32 v11, s1
	v_fmac_f32_e32 v11, s0, v9
	v_cvt_pk_bf16_f32 v9, v11, v11
	v_readlane_b32 s1, v3, 51
	v_fmac_f32_e32 v24, 0xbb800000, v5
	ds_write_b16 v202, v9 offset:13600
	v_readlane_b32 s0, v1, 51
	v_mul_f32_e32 v9, v24, v7
	v_mov_b32_e32 v11, s1
	v_fmac_f32_e32 v11, s0, v9
	v_cvt_pk_bf16_f32 v9, v11, v11
	v_readlane_b32 s1, v3, 52
	v_fmac_f32_e32 v22, 0xbb800000, v5
	ds_write_b16 v202, v9 offset:13872
	v_readlane_b32 s0, v1, 52
	v_mul_f32_e32 v9, v22, v7
	v_mov_b32_e32 v11, s1
	v_fmac_f32_e32 v11, s0, v9
	v_cvt_pk_bf16_f32 v9, v11, v11
	v_readlane_b32 s1, v3, 53
	v_fmac_f32_e32 v20, 0xbb800000, v5
	ds_write_b16 v202, v9 offset:14144
	v_readlane_b32 s0, v1, 53
	v_mul_f32_e32 v9, v20, v7
	v_mov_b32_e32 v11, s1
	v_fmac_f32_e32 v11, s0, v9
	v_cvt_pk_bf16_f32 v9, v11, v11
	v_readlane_b32 s1, v3, 54
	v_fmac_f32_e32 v16, 0xbb800000, v5
	ds_write_b16 v202, v9 offset:14416
	v_readlane_b32 s0, v1, 54
	v_mul_f32_e32 v9, v16, v7
	v_mov_b32_e32 v11, s1
	v_fmac_f32_e32 v11, s0, v9
	v_cvt_pk_bf16_f32 v9, v11, v11
	v_readlane_b32 s1, v3, 55
	v_fmac_f32_e32 v12, 0xbb800000, v5
	ds_write_b16 v202, v9 offset:14688
	v_readlane_b32 s0, v1, 55
	v_mul_f32_e32 v9, v12, v7
	v_mov_b32_e32 v11, s1
	v_fmac_f32_e32 v11, s0, v9
	v_cvt_pk_bf16_f32 v9, v11, v11
	v_readlane_b32 s1, v3, 56
	v_fmac_f32_e32 v18, 0xbb800000, v5
	ds_write_b16 v202, v9 offset:14960
	v_readlane_b32 s0, v1, 56
	v_mul_f32_e32 v9, v18, v7
	v_mov_b32_e32 v11, s1
	v_fmac_f32_e32 v11, s0, v9
	v_cvt_pk_bf16_f32 v9, v11, v11
	v_readlane_b32 s1, v3, 57
	v_fmac_f32_e32 v14, 0xbb800000, v5
	ds_write_b16 v202, v9 offset:15232
	v_readlane_b32 s0, v1, 57
	v_mul_f32_e32 v9, v14, v7
	v_mov_b32_e32 v11, s1
	v_fmac_f32_e32 v11, s0, v9
	v_cvt_pk_bf16_f32 v9, v11, v11
	v_readlane_b32 s1, v3, 58
	v_fmac_f32_e32 v10, 0xbb800000, v5
	ds_write_b16 v202, v9 offset:15504
	v_readlane_b32 s0, v1, 58
	v_mul_f32_e32 v9, v10, v7
	v_mov_b32_e32 v10, s1
	v_fmac_f32_e32 v10, s0, v9
	v_cvt_pk_bf16_f32 v9, v10, v10
	v_readlane_b32 s1, v3, 59
	v_fmac_f32_e32 v8, 0xbb800000, v5
	ds_write_b16 v202, v9 offset:15776
	v_readlane_b32 s0, v1, 59
	v_mul_f32_e32 v8, v8, v7
	v_mov_b32_e32 v9, s1
	v_fmac_f32_e32 v9, s0, v8
	v_cvt_pk_bf16_f32 v8, v9, v9
	v_readlane_b32 s1, v3, 60
	v_fmac_f32_e32 v6, 0xbb800000, v5
	ds_write_b16 v202, v8 offset:16048
	v_readlane_b32 s0, v1, 60
	v_mul_f32_e32 v6, v6, v7
	v_mov_b32_e32 v8, s1
	v_fmac_f32_e32 v8, s0, v6
	v_cvt_pk_bf16_f32 v6, v8, v8
	v_readlane_b32 s1, v3, 61
	v_fmac_f32_e32 v4, 0xbb800000, v5
	ds_write_b16 v202, v6 offset:16320
	v_readlane_b32 s0, v1, 61
	v_mul_f32_e32 v4, v4, v7
	v_mov_b32_e32 v6, s1
	v_fmac_f32_e32 v6, s0, v4
	v_cvt_pk_bf16_f32 v4, v6, v6
	v_readlane_b32 s1, v3, 62
	v_fmac_f32_e32 v2, 0xbb800000, v5
	ds_write_b16 v202, v4 offset:16592
	v_readlane_b32 s0, v1, 62
	v_mul_f32_e32 v2, v2, v7
	v_mov_b32_e32 v4, s1
	v_readlane_b32 s1, v3, 63
	v_fmac_f32_e32 v0, 0xbb800000, v5
	v_fmac_f32_e32 v4, s0, v2
	v_readlane_b32 s0, v1, 63
	v_mul_f32_e32 v0, v0, v7
	v_mov_b32_e32 v1, s1
	v_cvt_pk_bf16_f32 v2, v4, v4
	ds_write_b16 v202, v2 offset:16864
	v_fmac_f32_e32 v1, s0, v0
	v_cvt_pk_bf16_f32 v0, v1, v1
	ds_write_b16 v202, v0 offset:17136
	s_waitcnt lgkmcnt(0)
	s_barrier
; #define LAS __attribute__((address_space(3)))
; __device__ __forceinline__ int crow(int r, int hi) { return (r & 3) + 8 * (r >> 2) + 4 * hi; }
; __device__ __forceinline__ void sg_item(int l, int chunk, LAS unsigned char* lds, const bf16_t* UB, const bf16_t* V2T, bf16_t* YC1, const bf16_t* Wb,
;                                         const float* sg_ln_g, const float* sg_ln_b, const float* sg_b, int lane, int wave) {
;     ...
;         const int g = wave & 3, dt = wave >> 2, q = lane & 31, hi = lane >> 5, c = 64 * g + 32 * dt + q;
;         const bf16_t* Wg = Wb + (size_t)g * 128 * 128;
;         const unsigned avoff = (unsigned)(q * 128 + 8 * hi) * 2u;
;         f32x16 acc[4] = {};
;         bf16x8 Bf[8];
; #pragma unroll
;         for (int ks = 0; ks < 8; ++ks) Bf[ks] = *(const LAS bf16x8*)(vT + c * VS + 16 * ks + 8 * hi);
; #pragma unroll
;         for (int i = 0; i < 4; ++i) {
; #pragma unroll
;             for (int kb = 0; kb < 2 * i + 2; kb += 4) {
;                 u32x4 af[4]; const void* pp[4];
; #pragma unroll
;                 for (int j = 0; j < 4; ++j) pp[j] = Wg + (size_t)(32 * i) * 128 + 16 * ((kb + j) < 2 * i + 2 ? (kb + j) : 0);
;                 ld_b128_s4(af, avoff, pp);
; #pragma unroll
;                 for (int j = 0; j < 4; ++j) if (kb + j < 2 * i + 2) acc[i] = __builtin_amdgcn_mfma_f32_32x32x16_bf16(__builtin_bit_cast(bf16x8, af[j]), Bf[kb + j], acc[i], 0, 0, 0);
;             }
;         }
;         const float sb_lo = sg_b[(l * 4 + g) * 128 + lane], sb_hi = sg_b[(l * 4 + g) * 128 + 64 + lane];
;         const unsigned uvoff = (unsigned)(4 * hi * BW + c) * 2u;
; #pragma unroll
;         for (int i = 0; i < 4; ++i) {
;             unsigned uu[16];
; #pragma unroll
;             for (int rb = 0; rb < 16; rb += 8) {
;                 unsigned raw[8]; const void* pp[8];
; #pragma unroll
;                 for (int j = 0; j < 8; ++j) pp[j] = UB + (r0 + 32 * i + crow(rb + j, 0)) * BW;
	ds_read_b128 v[0:3], v201
	ds_read_b128 v[72:75], v201 offset:32
	ds_read_b128 v[76:79], v201 offset:64
	ds_read_b128 v[80:83], v201 offset:96
	ds_read_b128 v[84:87], v201 offset:128
	ds_read_b128 v[88:91], v201 offset:160
	ds_read_b128 v[92:95], v201 offset:192
	ds_read_b128 v[96:99], v201 offset:224
	s_add_u32 s98, s92, s80
	s_addc_u32 s99, s93, s81
	global_load_ushort v112, v152, s[48:49]
	s_add_u32 s98, s98, 0x200
	s_addc_u32 s99, s99, 0
	global_load_ushort v113, v152, s[98:99]
	s_add_u32 s98, s98, 0x200
	s_addc_u32 s99, s99, 0
	global_load_ushort v114, v152, s[98:99]
	s_add_u32 s98, s98, 0x200
	s_addc_u32 s99, s99, 0
	global_load_ushort v115, v152, s[98:99]
	s_add_u32 s98, s98, 0xa00
	s_addc_u32 s99, s99, 0
	global_load_ushort v116, v152, s[98:99]
	s_add_u32 s98, s98, 0x200
	s_addc_u32 s99, s99, 0
	global_load_ushort v117, v152, s[98:99]
	s_add_u32 s98, s98, 0x200
	s_addc_u32 s99, s99, 0
	global_load_ushort v118, v152, s[98:99]
	s_add_u32 s98, s98, 0x200
	s_addc_u32 s99, s99, 0
	global_load_ushort v119, v152, s[98:99]
	s_add_u32 s98, s98, 0xa00
	s_addc_u32 s99, s99, 0
	global_load_ushort v120, v152, s[98:99]
	s_add_u32 s98, s98, 0x200
	s_addc_u32 s99, s99, 0
	global_load_ushort v121, v152, s[98:99]
	s_add_u32 s98, s98, 0x200
	s_addc_u32 s99, s99, 0
	global_load_ushort v122, v152, s[98:99]
	s_add_u32 s98, s98, 0x200
	s_addc_u32 s99, s99, 0
	global_load_ushort v123, v152, s[98:99]
	s_add_u32 s98, s98, 0xa00
	s_addc_u32 s99, s99, 0
	global_load_ushort v124, v152, s[98:99]
	s_add_u32 s98, s98, 0x200
	s_addc_u32 s99, s99, 0
	global_load_ushort v125, v152, s[98:99]
	s_add_u32 s98, s98, 0x200
	s_addc_u32 s99, s99, 0
	global_load_ushort v126, v152, s[98:99]
	s_add_u32 s98, s98, 0x200
	s_addc_u32 s99, s99, 0
	global_load_ushort v127, v152, s[98:99]
	s_add_u32 s98, s98, 0xa00
	s_addc_u32 s99, s99, 0
	global_load_ushort v128, v152, s[98:99]
	s_add_u32 s98, s98, 0x200
	s_addc_u32 s99, s99, 0
	global_load_ushort v129, v152, s[98:99]
	s_add_u32 s98, s98, 0x200
	s_addc_u32 s99, s99, 0
	global_load_ushort v130, v152, s[98:99]
	s_add_u32 s98, s98, 0x200
	s_addc_u32 s99, s99, 0
	global_load_ushort v131, v152, s[98:99]
	s_add_u32 s98, s98, 0xa00
	s_addc_u32 s99, s99, 0
	global_load_ushort v132, v152, s[98:99]
	s_add_u32 s98, s98, 0x200
	s_addc_u32 s99, s99, 0
	global_load_ushort v133, v152, s[98:99]
	s_add_u32 s98, s98, 0x200
	s_addc_u32 s99, s99, 0
	global_load_ushort v220, v152, s[98:99]
	s_add_u32 s98, s98, 0x200
	s_addc_u32 s99, s99, 0
	global_load_ushort v221, v152, s[98:99]
	s_add_u32 s98, s98, 0xa00
	s_addc_u32 s99, s99, 0
	global_load_ushort v222, v152, s[98:99]
	s_add_u32 s98, s98, 0x200
	s_addc_u32 s99, s99, 0
	global_load_ushort v223, v152, s[98:99]
	s_add_u32 s98, s98, 0x200
	s_addc_u32 s99, s99, 0
	global_load_ushort v224, v152, s[98:99]
	s_add_u32 s98, s98, 0x200
	s_addc_u32 s99, s99, 0
	global_load_ushort v225, v152, s[98:99]
	s_add_u32 s98, s98, 0xa00
	s_addc_u32 s99, s99, 0
	global_load_ushort v226, v152, s[98:99]
	s_add_u32 s98, s98, 0x200
	s_addc_u32 s99, s99, 0
	global_load_ushort v227, v152, s[98:99]
	s_add_u32 s98, s98, 0x200
	s_addc_u32 s99, s99, 0
	global_load_ushort v228, v152, s[98:99]
	s_add_u32 s98, s98, 0x200
	s_addc_u32 s99, s99, 0
	global_load_ushort v229, v152, s[98:99]
	s_nop 4
	global_load_dwordx4 v[4:7], v203, s[6:7]
	global_load_dwordx4 v[8:11], v203, s[8:9]
	global_load_dwordx4 v[12:15], v203, s[6:7]
	global_load_dwordx4 v[16:19], v203, s[6:7]
	s_waitcnt vmcnt(0)
	s_add_u32 s0, s92, s80
	s_waitcnt lgkmcnt(7)
	v_mfma_f32_32x32x16_bf16 v[48:63], v[4:7], v[0:3], 0
	s_addc_u32 s1, s93, s81
	s_waitcnt lgkmcnt(6)
	v_mfma_f32_32x32x16_bf16 v[48:63], v[8:11], v[72:75], v[48:63]
	s_nop 4
	global_load_dwordx4 v[4:7], v203, s[10:11]
	global_load_dwordx4 v[8:11], v203, s[16:17]
	global_load_dwordx4 v[12:15], v203, s[18:19]
	global_load_dwordx4 v[16:19], v203, s[20:21]
	s_waitcnt vmcnt(0)
	v_mfma_f32_32x32x16_bf16 v[32:47], v[4:7], v[0:3], 0
	v_mfma_f32_32x32x16_bf16 v[32:47], v[8:11], v[72:75], v[32:47]
	s_waitcnt lgkmcnt(5)
	v_mfma_f32_32x32x16_bf16 v[32:47], v[12:15], v[76:79], v[32:47]
	s_nop 4
	global_load_dwordx4 v[4:7], v203, s[22:23]
	global_load_dwordx4 v[8:11], v203, s[24:25]
	global_load_dwordx4 v[12:15], v203, s[26:27]
	global_load_dwordx4 v[100:103], v203, s[28:29]
	s_waitcnt vmcnt(0)
	s_waitcnt lgkmcnt(4)
	v_mfma_f32_32x32x16_bf16 v[32:47], v[16:19], v[80:83], v[32:47]
	v_mfma_f32_32x32x16_bf16 v[16:31], v[4:7], v[0:3], 0
	v_mfma_f32_32x32x16_bf16 v[16:31], v[8:11], v[72:75], v[16:31]
	v_mfma_f32_32x32x16_bf16 v[16:31], v[12:15], v[76:79], v[16:31]
	v_mfma_f32_32x32x16_bf16 v[16:31], v[100:103], v[80:83], v[16:31]
	s_nop 4
	global_load_dwordx4 v[4:7], v203, s[30:31]
	global_load_dwordx4 v[8:11], v203, s[34:35]
	global_load_dwordx4 v[12:15], v203, s[22:23]
	global_load_dwordx4 v[100:103], v203, s[22:23]
	s_waitcnt vmcnt(0)
	s_waitcnt lgkmcnt(3)
	v_mfma_f32_32x32x16_bf16 v[16:31], v[4:7], v[84:87], v[16:31]
	s_nop 4
	global_load_dwordx4 v[4:7], v203, s[36:37]
	global_load_dwordx4 v[100:103], v203, s[38:39]
	global_load_dwordx4 v[104:107], v203, s[68:69]
	global_load_dwordx4 v[108:111], v203, s[70:71]
	s_waitcnt vmcnt(0)
	s_waitcnt lgkmcnt(2)
	v_mfma_f32_32x32x16_bf16 v[16:31], v[8:11], v[88:91], v[16:31]
	v_mfma_f32_32x32x16_bf16 v[0:15], v[4:7], v[0:3], 0
	v_mfma_f32_32x32x16_bf16 v[0:15], v[100:103], v[72:75], v[0:15]
	v_mfma_f32_32x32x16_bf16 v[0:15], v[104:107], v[76:79], v[0:15]
	v_mfma_f32_32x32x16_bf16 v[0:15], v[108:111], v[80:83], v[0:15]
	s_nop 4
	global_load_dwordx4 v[72:75], v203, s[72:73]
	global_load_dwordx4 v[76:79], v203, s[74:75]
	global_load_dwordx4 v[80:83], v203, s[76:77]
	global_load_dwordx4 v[100:103], v203, s[78:79]
	s_waitcnt vmcnt(0)
; __device__ __forceinline__ bf16_t f2bf(float f) { return (bf16_t)(cvt_pk_bf16(f, f) & 0xffffu); }
; __device__ __forceinline__ int crow(int r, int hi) { return (r & 3) + 8 * (r >> 2) + 4 * hi; }
; __device__ __forceinline__ void sg_item(int l, int chunk, LAS unsigned char* lds, const bf16_t* UB, const bf16_t* V2T, bf16_t* YC1, const bf16_t* Wb,
;                                         const float* sg_ln_g, const float* sg_ln_b, const float* sg_b, int lane, int wave) {
;     ...
;         for (int i = 0; i < 4; ++i) {
; #pragma unroll
;             for (int kb = 0; kb < 2 * i + 2; kb += 4) {
;                 u32x4 af[4]; const void* pp[4];
; #pragma unroll
;                 for (int j = 0; j < 4; ++j) pp[j] = Wg + (size_t)(32 * i) * 128 + 16 * ((kb + j) < 2 * i + 2 ? (kb + j) : 0);
;                 ld_b128_s4(af, avoff, pp);
; #pragma unroll
;                 for (int j = 0; j < 4; ++j) if (kb + j < 2 * i + 2) acc[i] = __builtin_amdgcn_mfma_f32_32x32x16_bf16(__builtin_bit_cast(bf16x8, af[j]), Bf[kb + j], acc[i], 0, 0, 0);
;             }
;         }
;         const float sb_lo = sg_b[(l * 4 + g) * 128 + lane], sb_hi = sg_b[(l * 4 + g) * 128 + 64 + lane];
;         const unsigned uvoff = (unsigned)(4 * hi * BW + c) * 2u;
; #pragma unroll
;         for (int i = 0; i < 4; ++i) {
;             unsigned uu[16];
; #pragma unroll
;             for (int rb = 0; rb < 16; rb += 8) {
;                 unsigned raw[8]; const void* pp[8];
; #pragma unroll
;                 for (int j = 0; j < 8; ++j) pp[j] = UB + (r0 + 32 * i + crow(rb + j, 0)) * BW;
;                 ld_u16_s8(raw, uvoff, pp);
; #pragma unroll
;                 for (int j = 0; j < 8; ++j) uu[rb + j] = raw[j];
;             }
; #pragma unroll
;             for (int r = 0; r < 16; ++r) {
;                 const int t = 32 * i + crow(r, hi);
;                 const float sbv = __int_as_float(__builtin_amdgcn_ds_bpermute((t & 63) << 2, __float_as_int(i < 2 ? sb_lo : sb_hi)));
;                 YC1[(r0 + t) * BW + c] = f2bf(__uint_as_float(uu[r] << 16) * (acc[i][r] + sbv));
	s_nop 0
	v_mfma_f32_32x32x16_bf16 v[0:15], v[72:75], v[84:87], v[0:15]
	global_load_dword v75, v[68:69], off
	global_load_dword v74, v[68:69], off offset:256
	s_waitcnt vmcnt(1)
	ds_bpermute_b32 v73, v200, v75
	v_mfma_f32_32x32x16_bf16 v[0:15], v[76:79], v[88:91], v[0:15]
	s_waitcnt lgkmcnt(0)
	v_add_f32_e32 v48, v48, v73
	v_mfma_f32_32x32x16_bf16 v[0:15], v[80:83], v[92:95], v[0:15]
	s_waitcnt vmcnt(0)
	v_mov_b32_e32 v72, v112
	v_mov_b32_e32 v90, v113
	v_mov_b32_e32 v89, v114
	v_mov_b32_e32 v88, v115
	v_mov_b32_e32 v87, v116
	v_mov_b32_e32 v86, v117
	v_mov_b32_e32 v84, v118
	v_mov_b32_e32 v83, v119
	v_lshlrev_b32_e32 v72, 16, v72
	v_mul_f32_e32 v48, v48, v72
	v_lshl_add_u64 v[72:73], v[70:71], 0, s[80:81]
	v_add_co_u32_e32 v92, vcc, s12, v72
	s_nop 0
	v_addc_co_u32_e32 v93, vcc, 0, v73, vcc
	s_mov_b32 s12, 0xb401000
	v_add_co_u32_e32 v94, vcc, s12, v72
	s_waitcnt vmcnt(0)
	v_mov_b32_e32 v85, v120
	v_mov_b32_e32 v82, v121
	v_mov_b32_e32 v81, v122
	v_mov_b32_e32 v80, v123
	v_mov_b32_e32 v79, v124
	v_mov_b32_e32 v78, v125
	v_mov_b32_e32 v77, v126
	v_mov_b32_e32 v76, v127
	s_add_u32 s98, s98, 0xa00
	s_addc_u32 s99, s99, 0
	global_load_ushort v112, v152, s[98:99]
	s_add_u32 s98, s98, 0x200
	s_addc_u32 s99, s99, 0
	global_load_ushort v113, v152, s[98:99]
	s_add_u32 s98, s98, 0x200
	s_addc_u32 s99, s99, 0
	global_load_ushort v114, v152, s[98:99]
	s_add_u32 s98, s98, 0x200
	s_addc_u32 s99, s99, 0
	global_load_ushort v115, v152, s[98:99]
	s_add_u32 s98, s98, 0xa00
	s_addc_u32 s99, s99, 0
	global_load_ushort v116, v152, s[98:99]
	s_add_u32 s98, s98, 0x200
	s_addc_u32 s99, s99, 0
	global_load_ushort v117, v152, s[98:99]
	s_add_u32 s98, s98, 0x200
	s_addc_u32 s99, s99, 0
	global_load_ushort v118, v152, s[98:99]
	s_add_u32 s98, s98, 0x200
	s_addc_u32 s99, s99, 0
	global_load_ushort v119, v152, s[98:99]
	s_add_u32 s98, s98, 0xa00
	s_addc_u32 s99, s99, 0
	global_load_ushort v120, v152, s[98:99]
	s_add_u32 s98, s98, 0x200
	s_addc_u32 s99, s99, 0
	global_load_ushort v121, v152, s[98:99]
	s_add_u32 s98, s98, 0x200
	s_addc_u32 s99, s99, 0
	global_load_ushort v122, v152, s[98:99]
	s_add_u32 s98, s98, 0x200
	s_addc_u32 s99, s99, 0
	global_load_ushort v123, v152, s[98:99]
	s_add_u32 s98, s98, 0xa00
	s_addc_u32 s99, s99, 0
	global_load_ushort v124, v152, s[98:99]
	s_add_u32 s98, s98, 0x200
	s_addc_u32 s99, s99, 0
	global_load_ushort v125, v152, s[98:99]
	s_add_u32 s98, s98, 0x200
	s_addc_u32 s99, s99, 0
	global_load_ushort v126, v152, s[98:99]
	s_add_u32 s98, s98, 0x200
	s_addc_u32 s99, s99, 0
	global_load_ushort v127, v152, s[98:99]
	v_cvt_pk_bf16_f32 v48, v48, v48
	s_nop 0
	v_addc_co_u32_e32 v95, vcc, 0, v73, vcc
	global_store_short v[94:95], v48, off offset:-4096
	ds_bpermute_b32 v48, v204, v75
	v_lshlrev_b32_e32 v90, 16, v90
	s_mov_b32 s12, 0xb402000
	s_waitcnt lgkmcnt(0)
	v_add_f32_e32 v48, v49, v48
	v_mul_f32_e32 v48, v48, v90
	v_cvt_pk_bf16_f32 v48, v48, v48
	global_store_short v[92:93], v48, off offset:512
	ds_bpermute_b32 v48, v205, v75
	v_lshlrev_b32_e32 v49, 16, v89
	s_waitcnt lgkmcnt(0)
	v_add_f32_e32 v48, v50, v48
	v_mul_f32_e32 v48, v48, v49
	v_cvt_pk_bf16_f32 v48, v48, v48
	global_store_short v[92:93], v48, off offset:1024
	ds_bpermute_b32 v48, v206, v75
	v_lshlrev_b32_e32 v49, 16, v88
	s_waitcnt lgkmcnt(0)
	v_add_f32_e32 v48, v51, v48
	v_mul_f32_e32 v48, v48, v49
	v_cvt_pk_bf16_f32 v48, v48, v48
	global_store_short v[92:93], v48, off offset:1536
	ds_bpermute_b32 v48, v207, v75
	v_lshlrev_b32_e32 v49, 16, v87
	s_waitcnt lgkmcnt(0)
	v_add_f32_e32 v48, v52, v48
	v_mul_f32_e32 v48, v48, v49
	v_cvt_pk_bf16_f32 v48, v48, v48
	global_store_short v[94:95], v48, off
	ds_bpermute_b32 v48, v208, v75
	v_lshlrev_b32_e32 v49, 16, v86
	s_waitcnt lgkmcnt(0)
	v_add_f32_e32 v48, v53, v48
	v_mul_f32_e32 v48, v48, v49
	v_cvt_pk_bf16_f32 v48, v48, v48
	global_store_short v[94:95], v48, off offset:512
	ds_bpermute_b32 v48, v209, v75
	v_lshlrev_b32_e32 v49, 16, v84
	v_lshlrev_b32_e32 v53, 16, v82
	s_waitcnt lgkmcnt(0)
	v_add_f32_e32 v48, v54, v48
	v_mul_f32_e32 v48, v48, v49
	v_cvt_pk_bf16_f32 v48, v48, v48
	global_store_short v[94:95], v48, off offset:1024
	ds_bpermute_b32 v48, v210, v75
	v_lshlrev_b32_e32 v49, 16, v83
	v_mfma_f32_32x32x16_bf16 v[0:15], v[100:103], v[96:99], v[0:15]
	v_lshl_add_u64 v[70:71], v[70:71], 0, s[82:83]
	s_waitcnt lgkmcnt(0)
	v_add_f32_e32 v48, v55, v48
	v_mul_f32_e32 v48, v48, v49
	v_cvt_pk_bf16_f32 v48, v48, v48
	global_store_short v[94:95], v48, off offset:1536
	ds_bpermute_b32 v48, v211, v75
	v_lshlrev_b32_e32 v49, 16, v85
	s_waitcnt lgkmcnt(0)
	v_add_f32_e32 v48, v56, v48
	v_mul_f32_e32 v48, v48, v49
	v_cvt_pk_bf16_f32 v52, v48, v48
	v_add_co_u32_e32 v48, vcc, s12, v72
	s_mov_b32 s12, 0xb403000
	s_nop 0
	v_addc_co_u32_e32 v49, vcc, 0, v73, vcc
	v_add_co_u32_e32 v50, vcc, s12, v72
	s_mov_b32 s12, 0xb404000
	s_nop 0
	v_addc_co_u32_e32 v51, vcc, 0, v73, vcc
	global_store_short v[50:51], v52, off offset:-4096
	ds_bpermute_b32 v52, v212, v75
	s_waitcnt lgkmcnt(0)
	v_add_f32_e32 v52, v57, v52
	v_mul_f32_e32 v52, v52, v53
	v_cvt_pk_bf16_f32 v52, v52, v52
	global_store_short v[48:49], v52, off offset:512
	ds_bpermute_b32 v52, v213, v75
	v_lshlrev_b32_e32 v53, 16, v81
	s_waitcnt lgkmcnt(0)
	v_add_f32_e32 v52, v58, v52
	v_mul_f32_e32 v52, v52, v53
	v_cvt_pk_bf16_f32 v52, v52, v52
	global_store_short v[48:49], v52, off offset:1024
	ds_bpermute_b32 v52, v214, v75
	v_lshlrev_b32_e32 v53, 16, v80
	s_waitcnt lgkmcnt(0)
	v_add_f32_e32 v52, v59, v52
	v_mul_f32_e32 v52, v52, v53
	v_cvt_pk_bf16_f32 v52, v52, v52
	global_store_short v[48:49], v52, off offset:1536
	ds_bpermute_b32 v48, v215, v75
	v_lshlrev_b32_e32 v49, 16, v79
	s_waitcnt lgkmcnt(0)
; __device__ __forceinline__ bf16_t f2bf(float f) { return (bf16_t)(cvt_pk_bf16(f, f) & 0xffffu); }
; __device__ __forceinline__ int crow(int r, int hi) { return (r & 3) + 8 * (r >> 2) + 4 * hi; }
; __device__ __forceinline__ void sg_item(int l, int chunk, LAS unsigned char* lds, const bf16_t* UB, const bf16_t* V2T, bf16_t* YC1, const bf16_t* Wb,
;                                         const float* sg_ln_g, const float* sg_ln_b, const float* sg_b, int lane, int wave) {
;     ...
; #pragma unroll
;         for (int i = 0; i < 4; ++i) {
;             unsigned uu[16];
; #pragma unroll
;             for (int rb = 0; rb < 16; rb += 8) {
;                 unsigned raw[8]; const void* pp[8];
; #pragma unroll
;                 for (int j = 0; j < 8; ++j) pp[j] = UB + (r0 + 32 * i + crow(rb + j, 0)) * BW;
;                 ld_u16_s8(raw, uvoff, pp);
; #pragma unroll
;                 for (int j = 0; j < 8; ++j) uu[rb + j] = raw[j];
;             }
; #pragma unroll
;             for (int r = 0; r < 16; ++r) {
;                 const int t = 32 * i + crow(r, hi);
;                 const float sbv = __int_as_float(__builtin_amdgcn_ds_bpermute((t & 63) << 2, __float_as_int(i < 2 ? sb_lo : sb_hi)));
;                 YC1[(r0 + t) * BW + c] = f2bf(__uint_as_float(uu[r] << 16) * (acc[i][r] + sbv));
	v_add_f32_e32 v48, v60, v48
	v_mul_f32_e32 v48, v48, v49
	v_cvt_pk_bf16_f32 v48, v48, v48
	global_store_short v[50:51], v48, off
	ds_bpermute_b32 v48, v216, v75
	v_lshlrev_b32_e32 v49, 16, v78
	s_waitcnt lgkmcnt(0)
	v_add_f32_e32 v48, v61, v48
	v_mul_f32_e32 v48, v48, v49
	v_cvt_pk_bf16_f32 v48, v48, v48
	global_store_short v[50:51], v48, off offset:512
	ds_bpermute_b32 v48, v217, v75
	v_lshlrev_b32_e32 v49, 16, v77
	s_waitcnt lgkmcnt(0)
	v_add_f32_e32 v48, v62, v48
	v_mul_f32_e32 v48, v48, v49
	v_cvt_pk_bf16_f32 v48, v48, v48
	global_store_short v[50:51], v48, off offset:1024
	ds_bpermute_b32 v48, v218, v75
	v_lshlrev_b32_e32 v49, 16, v76
	ds_bpermute_b32 v76, v153, v75
	s_waitcnt lgkmcnt(1)
	v_add_f32_e32 v48, v63, v48
	v_mul_f32_e32 v48, v48, v49
	v_cvt_pk_bf16_f32 v48, v48, v48
	global_store_short v[50:51], v48, off offset:1536
	s_waitcnt vmcnt(63)
	v_mov_b32_e32 v63, v128
	v_mov_b32_e32 v62, v129
	v_mov_b32_e32 v61, v130
	v_mov_b32_e32 v60, v131
	v_mov_b32_e32 v59, v132
	v_mov_b32_e32 v58, v133
	v_mov_b32_e32 v56, v220
	v_mov_b32_e32 v55, v221
	s_waitcnt lgkmcnt(0)
	v_add_f32_e32 v32, v32, v76
	v_add_co_u32_e32 v76, vcc, s12, v72
	v_lshlrev_b32_e32 v63, 16, v63
	v_addc_co_u32_e32 v77, vcc, 0, v73, vcc
	s_mov_b32 s12, 0xb405000
	v_mul_f32_e32 v32, v32, v63
	v_add_co_u32_e32 v78, vcc, s12, v72
	s_waitcnt vmcnt(58)
	v_mov_b32_e32 v57, v222
	v_mov_b32_e32 v54, v223
	v_mov_b32_e32 v53, v224
	v_mov_b32_e32 v52, v225
	v_mov_b32_e32 v51, v226
	v_mov_b32_e32 v50, v227
	v_mov_b32_e32 v49, v228
	v_mov_b32_e32 v48, v229
	s_add_u32 s98, s98, 0xa00
	s_addc_u32 s99, s99, 0
	global_load_ushort v128, v152, s[98:99]
	s_add_u32 s98, s98, 0x200
	s_addc_u32 s99, s99, 0
	global_load_ushort v129, v152, s[98:99]
	s_add_u32 s98, s98, 0x200
	s_addc_u32 s99, s99, 0
	global_load_ushort v130, v152, s[98:99]
	s_add_u32 s98, s98, 0x200
	s_addc_u32 s99, s99, 0
	global_load_ushort v131, v152, s[98:99]
	s_add_u32 s98, s98, 0xa00
	s_addc_u32 s99, s99, 0
	global_load_ushort v132, v152, s[98:99]
	s_add_u32 s98, s98, 0x200
	s_addc_u32 s99, s99, 0
	global_load_ushort v133, v152, s[98:99]
	s_add_u32 s98, s98, 0x200
	s_addc_u32 s99, s99, 0
	global_load_ushort v220, v152, s[98:99]
	s_add_u32 s98, s98, 0x200
	s_addc_u32 s99, s99, 0
	global_load_ushort v221, v152, s[98:99]
	s_add_u32 s98, s98, 0xa00
	s_addc_u32 s99, s99, 0
	global_load_ushort v222, v152, s[98:99]
	s_add_u32 s98, s98, 0x200
	s_addc_u32 s99, s99, 0
	global_load_ushort v223, v152, s[98:99]
	s_add_u32 s98, s98, 0x200
	s_addc_u32 s99, s99, 0
	global_load_ushort v224, v152, s[98:99]
	s_add_u32 s98, s98, 0x200
	s_addc_u32 s99, s99, 0
	global_load_ushort v225, v152, s[98:99]
	s_add_u32 s98, s98, 0xa00
	s_addc_u32 s99, s99, 0
	global_load_ushort v226, v152, s[98:99]
	s_add_u32 s98, s98, 0x200
	s_addc_u32 s99, s99, 0
	global_load_ushort v227, v152, s[98:99]
	s_add_u32 s98, s98, 0x200
	s_addc_u32 s99, s99, 0
	global_load_ushort v228, v152, s[98:99]
	s_add_u32 s98, s98, 0x200
	s_addc_u32 s99, s99, 0
	global_load_ushort v229, v152, s[98:99]
	v_cvt_pk_bf16_f32 v32, v32, v32
	s_nop 0
	v_addc_co_u32_e32 v79, vcc, 0, v73, vcc
	global_store_short v[78:79], v32, off offset:-4096
	ds_bpermute_b32 v32, v154, v75
	v_lshlrev_b32_e32 v62, 16, v62
	s_mov_b32 s12, 0xb406000
	s_waitcnt lgkmcnt(0)
	v_add_f32_e32 v32, v33, v32
	v_mul_f32_e32 v32, v32, v62
	v_cvt_pk_bf16_f32 v32, v32, v32
	global_store_short v[76:77], v32, off offset:512
	ds_bpermute_b32 v32, v155, v75
	v_lshlrev_b32_e32 v33, 16, v61
	s_waitcnt lgkmcnt(0)
	v_add_f32_e32 v32, v34, v32
	v_mul_f32_e32 v32, v32, v33
	v_cvt_pk_bf16_f32 v32, v32, v32
	global_store_short v[76:77], v32, off offset:1024
	ds_bpermute_b32 v32, v157, v75
	v_lshlrev_b32_e32 v33, 16, v60
	s_waitcnt lgkmcnt(0)
	v_add_f32_e32 v32, v35, v32
	v_mul_f32_e32 v32, v32, v33
	v_cvt_pk_bf16_f32 v32, v32, v32
	global_store_short v[76:77], v32, off offset:1536
	ds_bpermute_b32 v32, v161, v75
	v_lshlrev_b32_e32 v33, 16, v59
	s_waitcnt lgkmcnt(0)
	v_add_f32_e32 v32, v36, v32
	v_mul_f32_e32 v32, v32, v33
	v_cvt_pk_bf16_f32 v32, v32, v32
	global_store_short v[78:79], v32, off
	ds_bpermute_b32 v32, v162, v75
	v_lshlrev_b32_e32 v33, 16, v58
	s_waitcnt lgkmcnt(0)
	v_add_f32_e32 v32, v37, v32
	v_mul_f32_e32 v32, v32, v33
	v_cvt_pk_bf16_f32 v32, v32, v32
	global_store_short v[78:79], v32, off offset:512
	ds_bpermute_b32 v32, v163, v75
	v_lshlrev_b32_e32 v33, 16, v56
	v_lshlrev_b32_e32 v37, 16, v54
	s_waitcnt lgkmcnt(0)
	v_add_f32_e32 v32, v38, v32
	v_mul_f32_e32 v32, v32, v33
	v_cvt_pk_bf16_f32 v32, v32, v32
	global_store_short v[78:79], v32, off offset:1024
	ds_bpermute_b32 v32, v164, v75
	v_lshlrev_b32_e32 v33, 16, v55
	s_waitcnt lgkmcnt(0)
	v_add_f32_e32 v32, v39, v32
	v_mul_f32_e32 v32, v32, v33
	v_cvt_pk_bf16_f32 v32, v32, v32
	global_store_short v[78:79], v32, off offset:1536
	ds_bpermute_b32 v32, v165, v75
	v_lshlrev_b32_e32 v33, 16, v57
	s_waitcnt lgkmcnt(0)
	v_add_f32_e32 v32, v40, v32
	v_mul_f32_e32 v32, v32, v33
	v_cvt_pk_bf16_f32 v36, v32, v32
	v_add_co_u32_e32 v32, vcc, s12, v72
	s_mov_b32 s12, 0xb407000
	s_nop 0
	v_addc_co_u32_e32 v33, vcc, 0, v73, vcc
	v_add_co_u32_e32 v34, vcc, s12, v72
	s_mov_b32 s12, 0xb408000
	s_nop 0
	v_addc_co_u32_e32 v35, vcc, 0, v73, vcc
	global_store_short v[34:35], v36, off offset:-4096
	ds_bpermute_b32 v36, v166, v75
	s_waitcnt lgkmcnt(0)
	v_add_f32_e32 v36, v41, v36
	v_mul_f32_e32 v36, v36, v37
	v_cvt_pk_bf16_f32 v36, v36, v36
	global_store_short v[32:33], v36, off offset:512
	ds_bpermute_b32 v36, v167, v75
	v_lshlrev_b32_e32 v37, 16, v53
	s_waitcnt lgkmcnt(0)
	v_add_f32_e32 v36, v42, v36
	v_mul_f32_e32 v36, v36, v37
	v_cvt_pk_bf16_f32 v36, v36, v36
	global_store_short v[32:33], v36, off offset:1024
	ds_bpermute_b32 v36, v168, v75
	v_lshlrev_b32_e32 v37, 16, v52
	s_waitcnt lgkmcnt(0)
; __device__ __forceinline__ bf16_t f2bf(float f) { return (bf16_t)(cvt_pk_bf16(f, f) & 0xffffu); }
; __device__ __forceinline__ int crow(int r, int hi) { return (r & 3) + 8 * (r >> 2) + 4 * hi; }
; __device__ __forceinline__ void sg_item(int l, int chunk, LAS unsigned char* lds, const bf16_t* UB, const bf16_t* V2T, bf16_t* YC1, const bf16_t* Wb,
;                                         const float* sg_ln_g, const float* sg_ln_b, const float* sg_b, int lane, int wave) {
;     ...
; #pragma unroll
;         for (int i = 0; i < 4; ++i) {
;             unsigned uu[16];
; #pragma unroll
;             for (int rb = 0; rb < 16; rb += 8) {
;                 unsigned raw[8]; const void* pp[8];
; #pragma unroll
;                 for (int j = 0; j < 8; ++j) pp[j] = UB + (r0 + 32 * i + crow(rb + j, 0)) * BW;
;                 ld_u16_s8(raw, uvoff, pp);
; #pragma unroll
;                 for (int j = 0; j < 8; ++j) uu[rb + j] = raw[j];
;             }
; #pragma unroll
;             for (int r = 0; r < 16; ++r) {
;                 const int t = 32 * i + crow(r, hi);
;                 const float sbv = __int_as_float(__builtin_amdgcn_ds_bpermute((t & 63) << 2, __float_as_int(i < 2 ? sb_lo : sb_hi)));
;                 YC1[(r0 + t) * BW + c] = f2bf(__uint_as_float(uu[r] << 16) * (acc[i][r] + sbv));
	v_add_f32_e32 v36, v43, v36
	v_mul_f32_e32 v36, v36, v37
	v_cvt_pk_bf16_f32 v36, v36, v36
	global_store_short v[32:33], v36, off offset:1536
	ds_bpermute_b32 v32, v169, v75
	v_lshlrev_b32_e32 v33, 16, v51
	s_waitcnt lgkmcnt(0)
	v_add_f32_e32 v32, v44, v32
	v_mul_f32_e32 v32, v32, v33
	v_cvt_pk_bf16_f32 v32, v32, v32
	global_store_short v[34:35], v32, off
	ds_bpermute_b32 v32, v170, v75
	v_lshlrev_b32_e32 v33, 16, v50
	s_waitcnt lgkmcnt(0)
	v_add_f32_e32 v32, v45, v32
	v_mul_f32_e32 v32, v32, v33
	v_cvt_pk_bf16_f32 v32, v32, v32
	global_store_short v[34:35], v32, off offset:512
	ds_bpermute_b32 v32, v171, v75
	v_lshlrev_b32_e32 v33, 16, v49
	s_waitcnt lgkmcnt(0)
	v_add_f32_e32 v32, v46, v32
	v_mul_f32_e32 v32, v32, v33
	v_cvt_pk_bf16_f32 v32, v32, v32
	global_store_short v[34:35], v32, off offset:1024
	ds_bpermute_b32 v32, v172, v75
	v_lshlrev_b32_e32 v33, 16, v48
	s_waitcnt vmcnt(31)
	ds_bpermute_b32 v48, v200, v74
	s_waitcnt lgkmcnt(1)
	v_add_f32_e32 v32, v47, v32
	v_mul_f32_e32 v32, v32, v33
	v_cvt_pk_bf16_f32 v32, v32, v32
	global_store_short v[34:35], v32, off offset:1536
	s_waitcnt vmcnt(56)
	v_mov_b32_e32 v47, v112
	v_mov_b32_e32 v46, v113
	v_mov_b32_e32 v45, v114
	v_mov_b32_e32 v44, v115
	v_mov_b32_e32 v43, v116
	v_mov_b32_e32 v42, v117
	v_mov_b32_e32 v40, v118
	v_mov_b32_e32 v39, v119
	s_waitcnt lgkmcnt(0)
	v_add_f32_e32 v16, v16, v48
	v_add_co_u32_e32 v48, vcc, s12, v72
	v_lshlrev_b32_e32 v47, 16, v47
	v_addc_co_u32_e32 v49, vcc, 0, v73, vcc
	s_mov_b32 s12, 0xb409000
	v_mul_f32_e32 v16, v16, v47
	v_add_co_u32_e32 v50, vcc, s12, v72
	s_waitcnt vmcnt(48)
	v_mov_b32_e32 v41, v120
	v_mov_b32_e32 v38, v121
	v_mov_b32_e32 v37, v122
	v_mov_b32_e32 v36, v123
	v_mov_b32_e32 v35, v124
	v_mov_b32_e32 v34, v125
	v_mov_b32_e32 v33, v126
	v_mov_b32_e32 v32, v127
	v_cvt_pk_bf16_f32 v16, v16, v16
	s_nop 0
	v_addc_co_u32_e32 v51, vcc, 0, v73, vcc
	global_store_short v[50:51], v16, off offset:-4096
	ds_bpermute_b32 v16, v173, v74
	v_lshlrev_b32_e32 v46, 16, v46
	s_mov_b32 s12, 0xb40a000
	s_waitcnt lgkmcnt(0)
	v_add_f32_e32 v16, v17, v16
	v_mul_f32_e32 v16, v16, v46
	v_cvt_pk_bf16_f32 v16, v16, v16
	global_store_short v[48:49], v16, off offset:512
	ds_bpermute_b32 v16, v174, v74
	v_lshlrev_b32_e32 v17, 16, v45
	s_waitcnt lgkmcnt(0)
	v_add_f32_e32 v16, v18, v16
	v_mul_f32_e32 v16, v16, v17
	v_cvt_pk_bf16_f32 v16, v16, v16
	global_store_short v[48:49], v16, off offset:1024
	ds_bpermute_b32 v16, v175, v74
	v_lshlrev_b32_e32 v17, 16, v44
	s_waitcnt lgkmcnt(0)
	v_add_f32_e32 v16, v19, v16
	v_mul_f32_e32 v16, v16, v17
	v_cvt_pk_bf16_f32 v16, v16, v16
	global_store_short v[48:49], v16, off offset:1536
	ds_bpermute_b32 v16, v176, v74
	v_lshlrev_b32_e32 v17, 16, v43
	s_waitcnt lgkmcnt(0)
	v_add_f32_e32 v16, v20, v16
	v_mul_f32_e32 v16, v16, v17
	v_cvt_pk_bf16_f32 v16, v16, v16
	global_store_short v[50:51], v16, off
	ds_bpermute_b32 v16, v177, v74
	v_lshlrev_b32_e32 v17, 16, v42
	s_waitcnt lgkmcnt(0)
	v_add_f32_e32 v16, v21, v16
	v_mul_f32_e32 v16, v16, v17
	v_cvt_pk_bf16_f32 v16, v16, v16
	global_store_short v[50:51], v16, off offset:512
	ds_bpermute_b32 v16, v178, v74
	v_lshlrev_b32_e32 v17, 16, v40
	v_lshlrev_b32_e32 v21, 16, v38
	s_waitcnt lgkmcnt(0)
	v_add_f32_e32 v16, v22, v16
	v_mul_f32_e32 v16, v16, v17
	v_cvt_pk_bf16_f32 v16, v16, v16
	global_store_short v[50:51], v16, off offset:1024
	ds_bpermute_b32 v16, v179, v74
	v_lshlrev_b32_e32 v17, 16, v39
	s_waitcnt lgkmcnt(0)
	v_add_f32_e32 v16, v23, v16
	v_mul_f32_e32 v16, v16, v17
	v_cvt_pk_bf16_f32 v16, v16, v16
	global_store_short v[50:51], v16, off offset:1536
	ds_bpermute_b32 v16, v180, v74
	v_lshlrev_b32_e32 v17, 16, v41
	s_waitcnt lgkmcnt(0)
	v_add_f32_e32 v16, v24, v16
	v_mul_f32_e32 v16, v16, v17
	v_cvt_pk_bf16_f32 v20, v16, v16
	v_add_co_u32_e32 v16, vcc, s12, v72
	s_mov_b32 s12, 0xb40b000
	s_nop 0
	v_addc_co_u32_e32 v17, vcc, 0, v73, vcc
	v_add_co_u32_e32 v18, vcc, s12, v72
	s_nop 1
	v_addc_co_u32_e32 v19, vcc, 0, v73, vcc
	global_store_short v[18:19], v20, off offset:-4096
	ds_bpermute_b32 v20, v181, v74
	s_waitcnt lgkmcnt(0)
	v_add_f32_e32 v20, v25, v20
	v_mul_f32_e32 v20, v20, v21
	v_cvt_pk_bf16_f32 v20, v20, v20
	global_store_short v[16:17], v20, off offset:512
	ds_bpermute_b32 v20, v182, v74
	v_lshlrev_b32_e32 v21, 16, v37
	s_waitcnt lgkmcnt(0)
	v_add_f32_e32 v20, v26, v20
	v_mul_f32_e32 v20, v20, v21
	v_cvt_pk_bf16_f32 v20, v20, v20
	global_store_short v[16:17], v20, off offset:1024
	ds_bpermute_b32 v20, v183, v74
	v_lshlrev_b32_e32 v21, 16, v36
	s_waitcnt lgkmcnt(0)
	v_add_f32_e32 v20, v27, v20
	v_mul_f32_e32 v20, v20, v21
	v_cvt_pk_bf16_f32 v20, v20, v20
	global_store_short v[16:17], v20, off offset:1536
	ds_bpermute_b32 v16, v184, v74
	v_lshlrev_b32_e32 v17, 16, v35
	s_waitcnt lgkmcnt(0)
	v_add_f32_e32 v16, v28, v16
	v_mul_f32_e32 v16, v16, v17
	v_cvt_pk_bf16_f32 v16, v16, v16
	global_store_short v[18:19], v16, off
	ds_bpermute_b32 v16, v185, v74
	v_lshlrev_b32_e32 v17, 16, v34
	s_waitcnt lgkmcnt(0)
	v_add_f32_e32 v16, v29, v16
	v_mul_f32_e32 v16, v16, v17
	v_cvt_pk_bf16_f32 v16, v16, v16
	global_store_short v[18:19], v16, off offset:512
	ds_bpermute_b32 v16, v186, v74
	v_lshlrev_b32_e32 v17, 16, v33
	s_waitcnt lgkmcnt(0)
; __device__ __forceinline__ bf16_t f2bf(float f) { return (bf16_t)(cvt_pk_bf16(f, f) & 0xffffu); }
; __device__ __forceinline__ int crow(int r, int hi) { return (r & 3) + 8 * (r >> 2) + 4 * hi; }
; __device__ __forceinline__ void sg_item(int l, int chunk, LAS unsigned char* lds, const bf16_t* UB, const bf16_t* V2T, bf16_t* YC1, const bf16_t* Wb,
;                                         const float* sg_ln_g, const float* sg_ln_b, const float* sg_b, int lane, int wave) {
;     ...
; #pragma unroll
;         for (int i = 0; i < 4; ++i) {
;             unsigned uu[16];
; #pragma unroll
;             for (int rb = 0; rb < 16; rb += 8) {
;                 unsigned raw[8]; const void* pp[8];
; #pragma unroll
;                 for (int j = 0; j < 8; ++j) pp[j] = UB + (r0 + 32 * i + crow(rb + j, 0)) * BW;
;                 ld_u16_s8(raw, uvoff, pp);
; #pragma unroll
;                 for (int j = 0; j < 8; ++j) uu[rb + j] = raw[j];
;             }
; #pragma unroll
;             for (int r = 0; r < 16; ++r) {
;                 const int t = 32 * i + crow(r, hi);
;                 const float sbv = __int_as_float(__builtin_amdgcn_ds_bpermute((t & 63) << 2, __float_as_int(i < 2 ? sb_lo : sb_hi)));
;                 YC1[(r0 + t) * BW + c] = f2bf(__uint_as_float(uu[r] << 16) * (acc[i][r] + sbv));
;             }
;         }
;     }
;     __syncthreads();
	v_add_f32_e32 v16, v30, v16
	v_mul_f32_e32 v16, v16, v17
	v_cvt_pk_bf16_f32 v16, v16, v16
	global_store_short v[18:19], v16, off offset:1024
	ds_bpermute_b32 v16, v187, v74
	v_lshlrev_b32_e32 v17, 16, v32
	ds_bpermute_b32 v32, v188, v74
	s_waitcnt lgkmcnt(1)
	v_add_f32_e32 v16, v31, v16
	v_mul_f32_e32 v16, v16, v17
	v_cvt_pk_bf16_f32 v16, v16, v16
	global_store_short v[18:19], v16, off offset:1536
	s_waitcnt vmcnt(40)
	v_mov_b32_e32 v31, v128
	v_mov_b32_e32 v30, v129
	v_mov_b32_e32 v29, v130
	v_mov_b32_e32 v28, v131
	v_mov_b32_e32 v27, v132
	v_mov_b32_e32 v26, v133
	v_mov_b32_e32 v24, v220
	v_mov_b32_e32 v23, v221
	s_add_u32 s0, s0, 0xf600
	s_addc_u32 s1, s1, 0
	s_waitcnt vmcnt(32)
	v_mov_b32_e32 v25, v222
	v_mov_b32_e32 v22, v223
	v_mov_b32_e32 v21, v224
	v_mov_b32_e32 v20, v225
	v_mov_b32_e32 v19, v226
	v_mov_b32_e32 v18, v227
	v_mov_b32_e32 v17, v228
	v_mov_b32_e32 v16, v229
	s_mov_b32 s0, 0xb40c000
	s_waitcnt lgkmcnt(0)
	v_add_f32_e32 v0, v0, v32
	v_add_co_u32_e32 v32, vcc, s0, v72
	v_lshlrev_b32_e32 v31, 16, v31
	s_nop 0
	v_addc_co_u32_e32 v33, vcc, 0, v73, vcc
	s_mov_b32 s0, 0xb40d000
	v_mul_f32_e32 v0, v0, v31
	v_add_co_u32_e32 v34, vcc, s0, v72
	v_cvt_pk_bf16_f32 v0, v0, v0
	v_lshlrev_b32_e32 v30, 16, v30
	s_nop 0
	v_addc_co_u32_e32 v35, vcc, 0, v73, vcc
	global_store_short v[34:35], v0, off offset:-4096
	ds_bpermute_b32 v0, v189, v74
	s_mov_b32 s0, 0xb40e000
	s_add_i32 s13, s13, s96
	s_add_u32 s92, s92, s82
	s_addc_u32 s93, s93, s83
	s_waitcnt lgkmcnt(0)
	v_add_f32_e32 v0, v1, v0
	v_mul_f32_e32 v0, v0, v30
	v_cvt_pk_bf16_f32 v0, v0, v0
	global_store_short v[32:33], v0, off offset:512
	ds_bpermute_b32 v0, v190, v74
	v_lshlrev_b32_e32 v1, 16, v29
	s_add_u32 s4, s4, s82
	s_addc_u32 s5, s5, s83
	s_add_u32 s84, s84, s86
	s_waitcnt lgkmcnt(0)
	v_add_f32_e32 v0, v2, v0
	v_mul_f32_e32 v0, v0, v1
	v_cvt_pk_bf16_f32 v0, v0, v0
	global_store_short v[32:33], v0, off offset:1024
	ds_bpermute_b32 v0, v157, v74
	v_lshlrev_b32_e32 v1, 16, v28
	s_addc_u32 s85, s85, s87
	s_add_u32 s88, s88, s90
	s_addc_u32 s89, s89, s91
	s_waitcnt lgkmcnt(0)
	v_add_f32_e32 v0, v3, v0
	v_mul_f32_e32 v0, v0, v1
	v_cvt_pk_bf16_f32 v0, v0, v0
	global_store_short v[32:33], v0, off offset:1536
	ds_bpermute_b32 v0, v191, v74
	v_lshlrev_b32_e32 v1, 16, v27
	v_lshlrev_b32_e32 v3, 16, v22
	s_cmpk_gt_i32 s13, 0xff
	s_waitcnt lgkmcnt(0)
	v_add_f32_e32 v0, v4, v0
	v_mul_f32_e32 v0, v0, v1
	v_cvt_pk_bf16_f32 v0, v0, v0
	global_store_short v[34:35], v0, off
	ds_bpermute_b32 v0, v192, v74
	v_lshlrev_b32_e32 v1, 16, v26
	s_waitcnt lgkmcnt(0)
	v_add_f32_e32 v0, v5, v0
	v_mul_f32_e32 v0, v0, v1
	v_cvt_pk_bf16_f32 v0, v0, v0
	global_store_short v[34:35], v0, off offset:512
	ds_bpermute_b32 v0, v193, v74
	v_lshlrev_b32_e32 v1, 16, v24
	s_waitcnt lgkmcnt(0)
	v_add_f32_e32 v0, v6, v0
	v_mul_f32_e32 v0, v0, v1
	v_cvt_pk_bf16_f32 v0, v0, v0
	global_store_short v[34:35], v0, off offset:1024
	ds_bpermute_b32 v0, v164, v74
	v_lshlrev_b32_e32 v1, 16, v23
	s_waitcnt lgkmcnt(0)
	v_add_f32_e32 v0, v7, v0
	v_mul_f32_e32 v0, v0, v1
	v_cvt_pk_bf16_f32 v0, v0, v0
	global_store_short v[34:35], v0, off offset:1536
	ds_bpermute_b32 v0, v194, v74
	v_lshlrev_b32_e32 v1, 16, v25
	s_waitcnt lgkmcnt(0)
	v_add_f32_e32 v0, v8, v0
	v_mul_f32_e32 v0, v0, v1
	v_cvt_pk_bf16_f32 v2, v0, v0
	v_add_co_u32_e32 v0, vcc, s0, v72
	s_mov_b32 s0, 0xb40f000
	s_nop 0
	v_addc_co_u32_e32 v1, vcc, 0, v73, vcc
	v_add_co_u32_e32 v4, vcc, s0, v72
	s_nop 1
	v_addc_co_u32_e32 v5, vcc, 0, v73, vcc
	global_store_short v[4:5], v2, off offset:-4096
	ds_bpermute_b32 v2, v195, v74
	s_waitcnt lgkmcnt(0)
	v_add_f32_e32 v2, v9, v2
	v_mul_f32_e32 v2, v2, v3
	v_cvt_pk_bf16_f32 v2, v2, v2
	global_store_short v[0:1], v2, off offset:512
	ds_bpermute_b32 v2, v196, v74
	v_lshlrev_b32_e32 v3, 16, v21
	s_waitcnt lgkmcnt(0)
	v_add_f32_e32 v2, v10, v2
	v_mul_f32_e32 v2, v2, v3
	v_cvt_pk_bf16_f32 v2, v2, v2
	global_store_short v[0:1], v2, off offset:1024
	ds_bpermute_b32 v2, v168, v74
	v_lshlrev_b32_e32 v3, 16, v20
	s_waitcnt lgkmcnt(0)
	v_add_f32_e32 v2, v11, v2
	v_mul_f32_e32 v2, v2, v3
	v_cvt_pk_bf16_f32 v2, v2, v2
	global_store_short v[0:1], v2, off offset:1536
	ds_bpermute_b32 v0, v197, v74
	v_lshlrev_b32_e32 v1, 16, v19
	s_waitcnt lgkmcnt(0)
	v_add_f32_e32 v0, v12, v0
	v_mul_f32_e32 v0, v0, v1
	v_cvt_pk_bf16_f32 v0, v0, v0
	global_store_short v[4:5], v0, off
	ds_bpermute_b32 v0, v198, v74
	v_lshlrev_b32_e32 v1, 16, v18
	s_waitcnt lgkmcnt(0)
	v_add_f32_e32 v0, v13, v0
	v_mul_f32_e32 v0, v0, v1
	v_cvt_pk_bf16_f32 v0, v0, v0
	global_store_short v[4:5], v0, off offset:512
	ds_bpermute_b32 v0, v199, v74
	v_lshlrev_b32_e32 v1, 16, v17
	s_waitcnt lgkmcnt(0)
	v_add_f32_e32 v0, v14, v0
	v_mul_f32_e32 v0, v0, v1
	v_cvt_pk_bf16_f32 v0, v0, v0
	global_store_short v[4:5], v0, off offset:1024
	ds_bpermute_b32 v0, v172, v74
	v_lshlrev_b32_e32 v1, 16, v16
	s_waitcnt lgkmcnt(0)
	v_add_f32_e32 v0, v15, v0
	v_mul_f32_e32 v0, v0, v1
	v_cvt_pk_bf16_f32 v0, v0, v0
	global_store_short v[4:5], v0, off offset:1536
	s_waitcnt vmcnt(63) expcnt(7) lgkmcnt(15)
	s_barrier
	s_cbranch_scc0 .LBB0_79
